# P11 (mLSTM pass C) epilogue: the 8 serialized norm_w row loads issued together (on top of v6d; v7 P7 remap dropped)
# speedup vs baseline: 1.0093x; 1.0093x over previous
; #define LAS __attribute__((address_space(3)))
; #define MFMA16(a, b, c) __builtin_amdgcn_mfma_f32_16x16x32_bf16((a), (b), (c), 0, 0, 0)
; __device__ __forceinline__ void mlstm_passC(LAS unsigned char* lds, const bf16_t* Z, const float* G, const float* conv_w, const float* conv_b, const float* b_i, const float* b_f, ...
;     ...
;     bf16x8 qa[4];
; #pragma unroll
;     for (int kk = 0; kk < 4; ++kk) qa[kk] = *(const LAS bf16x8*)(Qs + (wid * 16 + fr) * LROW + kk * 32 + fq * 8);
;     f32x4 S[8];
; #pragma unroll
;     for (int n = 0; n < 8; ++n) S[n] = (f32x4){0.f, 0.f, 0.f, 0.f};
; #pragma unroll
;     for (int kk = 0; kk < 4; ++kk)
; #pragma unroll
;         for (int n = 0; n < 8; ++n) { const bf16x8 b = *(const LAS bf16x8*)(Ks + (n * 16 + fr) * LROW + kk * 32 + fq * 8); S[n] = MFMA16(b, qa[kk], S[n]); }
;     __syncthreads();
.LBB0_980:
	s_or_b64 exec, exec, s[66:67]
	v_add_u32_e32 v98, v168, v108
	v_add_u32_e32 v80, v169, v170
	ds_read_b128 v[60:63], v98
	ds_read_b128 v[56:59], v98 offset:64
	ds_read_b128 v[52:55], v98 offset:128
	ds_read_b128 v[48:51], v98 offset:192
	s_waitcnt lgkmcnt(4)
	ds_read_b128 v[16:19], v80 offset:34816
	ds_read_b128 v[64:67], v80 offset:34880
	ds_read_b128 v[20:23], v80 offset:39168
	ds_read_b128 v[24:27], v80 offset:43520
	ds_read_b128 v[28:31], v80 offset:47872
	ds_read_b128 v[32:35], v80 offset:52224
	v_add_u32_e32 v81, v169, v171
	s_waitcnt lgkmcnt(5)
	v_mfma_f32_16x16x32_bf16 v[16:19], v[16:19], v[60:63], 0
	ds_read_b128 v[36:39], v81 offset:34816
	ds_read_b128 v[40:43], v81 offset:39168
	ds_read_b128 v[44:47], v81 offset:43520
	s_waitcnt lgkmcnt(7)
	v_mfma_f32_16x16x32_bf16 v[16:19], v[64:67], v[56:59], v[16:19]
	ds_read_b128 v[64:67], v80 offset:39232
	v_add_u32_e32 v92, v172, v173
	v_add_u32_e32 v119, v172, v175
	s_waitcnt lgkmcnt(7)
	v_mfma_f32_16x16x32_bf16 v[20:23], v[20:23], v[60:63], 0
	v_add3_u32 v115, 0, v115, v118
	v_readlane_b32 s8, v252, 40
	v_readlane_b32 s9, v252, 41
	s_waitcnt lgkmcnt(0)
	v_mfma_f32_16x16x32_bf16 v[20:23], v[64:67], v[56:59], v[20:23]
	ds_read_b128 v[64:67], v80 offset:43584
	s_add_i32 s2, s2, s76
	v_mfma_f32_16x16x32_bf16 v[24:27], v[24:27], v[60:63], 0
	s_waitcnt lgkmcnt(0)
	v_mfma_f32_16x16x32_bf16 v[24:27], v[64:67], v[56:59], v[24:27]
	ds_read_b128 v[64:67], v80 offset:47936
	v_mfma_f32_16x16x32_bf16 v[28:31], v[28:31], v[60:63], 0
	s_waitcnt lgkmcnt(0)
	v_mfma_f32_16x16x32_bf16 v[28:31], v[64:67], v[56:59], v[28:31]
	ds_read_b128 v[64:67], v80 offset:52288
	v_mfma_f32_16x16x32_bf16 v[32:35], v[32:35], v[60:63], 0
	s_waitcnt lgkmcnt(0)
	v_mfma_f32_16x16x32_bf16 v[32:35], v[64:67], v[56:59], v[32:35]
	ds_read_b128 v[64:67], v81 offset:34880
	v_mfma_f32_16x16x32_bf16 v[36:39], v[36:39], v[60:63], 0
	s_waitcnt lgkmcnt(0)
	v_mfma_f32_16x16x32_bf16 v[36:39], v[64:67], v[56:59], v[36:39]
	ds_read_b128 v[64:67], v81 offset:39232
	v_mfma_f32_16x16x32_bf16 v[40:43], v[40:43], v[60:63], 0
	s_waitcnt lgkmcnt(0)
	v_mfma_f32_16x16x32_bf16 v[40:43], v[64:67], v[56:59], v[40:43]
	ds_read_b128 v[64:67], v81 offset:43584
	v_mfma_f32_16x16x32_bf16 v[44:47], v[44:47], v[60:63], 0
	s_waitcnt lgkmcnt(0)
	v_mfma_f32_16x16x32_bf16 v[44:47], v[64:67], v[56:59], v[44:47]
	ds_read_b128 v[64:67], v80 offset:34944
	s_waitcnt lgkmcnt(0)
	v_mfma_f32_16x16x32_bf16 v[16:19], v[64:67], v[52:55], v[16:19]
	ds_read_b128 v[64:67], v80 offset:39296
	s_waitcnt lgkmcnt(0)
	v_mfma_f32_16x16x32_bf16 v[20:23], v[64:67], v[52:55], v[20:23]
	ds_read_b128 v[64:67], v80 offset:43648
	s_waitcnt lgkmcnt(0)
	v_mfma_f32_16x16x32_bf16 v[24:27], v[64:67], v[52:55], v[24:27]
	ds_read_b128 v[64:67], v80 offset:48000
	s_waitcnt lgkmcnt(0)
	v_mfma_f32_16x16x32_bf16 v[28:31], v[64:67], v[52:55], v[28:31]
	ds_read_b128 v[64:67], v80 offset:52352
	s_waitcnt lgkmcnt(0)
	v_mfma_f32_16x16x32_bf16 v[64:67], v[64:67], v[52:55], v[32:35]
	s_nop 2
	ds_read_b128 v[32:35], v81 offset:34944
	s_waitcnt lgkmcnt(0)
	v_mfma_f32_16x16x32_bf16 v[68:71], v[32:35], v[52:55], v[36:39]
	ds_read_b128 v[32:35], v81 offset:39296
	s_waitcnt lgkmcnt(0)
	v_mfma_f32_16x16x32_bf16 v[72:75], v[32:35], v[52:55], v[40:43]
	ds_read_b128 v[32:35], v81 offset:43648
	s_waitcnt lgkmcnt(0)
	v_mfma_f32_16x16x32_bf16 v[76:79], v[32:35], v[52:55], v[44:47]
	ds_read_b128 v[32:35], v80 offset:35008
	s_waitcnt lgkmcnt(0)
	v_mfma_f32_16x16x32_bf16 v[44:47], v[32:35], v[48:51], v[16:19]
	s_nop 2
	ds_read_b128 v[16:19], v80 offset:39360
	s_waitcnt lgkmcnt(0)
	v_mfma_f32_16x16x32_bf16 v[40:43], v[16:19], v[48:51], v[20:23]
	ds_read_b128 v[16:19], v80 offset:43712
	s_waitcnt lgkmcnt(0)
	v_mfma_f32_16x16x32_bf16 v[36:39], v[16:19], v[48:51], v[24:27]
	ds_read_b128 v[16:19], v80 offset:48064
	s_waitcnt lgkmcnt(0)
	v_mfma_f32_16x16x32_bf16 v[32:35], v[16:19], v[48:51], v[28:31]
	ds_read_b128 v[16:19], v80 offset:52416
	s_waitcnt lgkmcnt(0)
	v_mfma_f32_16x16x32_bf16 v[28:31], v[16:19], v[48:51], v[64:67]
	ds_read_b128 v[16:19], v81 offset:35008
	s_waitcnt lgkmcnt(0)
	v_mfma_f32_16x16x32_bf16 v[24:27], v[16:19], v[48:51], v[68:71]
	ds_read_b128 v[16:19], v81 offset:39360
	s_waitcnt lgkmcnt(0)
	v_mfma_f32_16x16x32_bf16 v[20:23], v[16:19], v[48:51], v[72:75]
	ds_read_b128 v[16:19], v81 offset:43712
	s_waitcnt lgkmcnt(0)
	s_barrier
; #define LAS __attribute__((address_space(3)))
; #define MFMA16(a, b, c) __builtin_amdgcn_mfma_f32_16x16x32_bf16((a), (b), (c), 0, 0, 0)
; __device__ __forceinline__ void mlstm_passC(LAS unsigned char* lds, const bf16_t* Z, const float* G, const float* conv_w, const float* conv_b, const float* b_i, const float* b_f, ...
;     ...
; #pragma unroll
;     for (int kk = 0; kk < 4; ++kk)
; #pragma unroll
;         for (int n = 0; n < 8; ++n) { const bf16x8 b0 = *(const LAS bf16x8*)(CF + (n * 16 + fr) * 256 + (((kk * 4 + fq) ^ fr) << 4)); Xf[n] = MFMA16(b0, qa[kk], Xf[n]); }
;     LAS unsigned char* CB = (LAS unsigned char*)Qs;
; #pragma unroll
;     for (int i = 0; i < 4; ++i) { const int q = tid + 512 * i, e = q >> 4, p = q & 15; *(LAS u32x4*)(CB + e * 256 + ((p ^ (e & 15)) << 4)) = cbr[i]; }
;     u32x4 ogr[4];
; #pragma unroll
;     for (int i = 0; i < 4; ++i) { const int q = lane + 64 * i; ogr[i] = *(const u32x4*)(Z + (size_t)(r0 + wid * 16 + (q >> 4)) * LDZ + 3072 + h * 128 + (q & 15) * 8); }
;     mlstm_dir<0>(S, Xf, hs, Ps, Vt, fl, wid, fr, fq);
	ds_read_b128 v[64:67], v92
	ds_read_b128 v[68:71], v92 offset:4096
	ds_read_b128 v[88:91], v92 offset:24576
	ds_read_b128 v[120:123], v119
	s_waitcnt lgkmcnt(3)
	v_mfma_f32_16x16x32_bf16 v[64:67], v[64:67], v[60:63], 0
	ds_read_b128 v[72:75], v92 offset:8192
	ds_read_b128 v[80:83], v92 offset:16384
	ds_read_b128 v[84:87], v92 offset:20480
	v_mfma_f32_16x16x32_bf16 v[16:19], v[16:19], v[48:51], v[76:79]
	s_nop 2
	ds_read_b128 v[76:79], v92 offset:12288
	ds_read_b128 v[92:95], v92 offset:28672
	s_waitcnt lgkmcnt(5)
	v_mfma_f32_16x16x32_bf16 v[64:67], v[120:123], v[56:59], v[64:67]
	ds_read_b128 v[120:123], v119 offset:4096
	v_mfma_f32_16x16x32_bf16 v[68:71], v[68:71], v[60:63], 0
	s_waitcnt lgkmcnt(0)
	v_mfma_f32_16x16x32_bf16 v[68:71], v[120:123], v[56:59], v[68:71]
	ds_read_b128 v[120:123], v119 offset:8192
	v_mfma_f32_16x16x32_bf16 v[72:75], v[72:75], v[60:63], 0
	s_waitcnt lgkmcnt(0)
	v_mfma_f32_16x16x32_bf16 v[72:75], v[120:123], v[56:59], v[72:75]
	ds_read_b128 v[120:123], v119 offset:12288
	v_mfma_f32_16x16x32_bf16 v[76:79], v[76:79], v[60:63], 0
	s_waitcnt lgkmcnt(0)
	v_mfma_f32_16x16x32_bf16 v[76:79], v[120:123], v[56:59], v[76:79]
	ds_read_b128 v[120:123], v119 offset:16384
	v_mfma_f32_16x16x32_bf16 v[80:83], v[80:83], v[60:63], 0
	s_waitcnt lgkmcnt(0)
	v_mfma_f32_16x16x32_bf16 v[80:83], v[120:123], v[56:59], v[80:83]
	ds_read_b128 v[120:123], v119 offset:20480
	v_mfma_f32_16x16x32_bf16 v[84:87], v[84:87], v[60:63], 0
	s_waitcnt lgkmcnt(0)
	v_mfma_f32_16x16x32_bf16 v[84:87], v[120:123], v[56:59], v[84:87]
	ds_read_b128 v[120:123], v119 offset:24576
	v_mfma_f32_16x16x32_bf16 v[88:91], v[88:91], v[60:63], 0
	s_waitcnt lgkmcnt(0)
	v_mfma_f32_16x16x32_bf16 v[88:91], v[120:123], v[56:59], v[88:91]
	ds_read_b128 v[120:123], v119 offset:28672
	v_add_u32_e32 v119, v172, v177
	v_mfma_f32_16x16x32_bf16 v[92:95], v[92:95], v[60:63], 0
	s_waitcnt lgkmcnt(0)
	v_mfma_f32_16x16x32_bf16 v[92:95], v[120:123], v[56:59], v[92:95]
	ds_read_b128 v[120:123], v119
	s_waitcnt lgkmcnt(0)
	v_mfma_f32_16x16x32_bf16 v[64:67], v[120:123], v[52:55], v[64:67]
	ds_read_b128 v[120:123], v119 offset:4096
	s_waitcnt lgkmcnt(0)
	v_mfma_f32_16x16x32_bf16 v[68:71], v[120:123], v[52:55], v[68:71]
	ds_read_b128 v[120:123], v119 offset:8192
	s_waitcnt lgkmcnt(0)
	v_mfma_f32_16x16x32_bf16 v[72:75], v[120:123], v[52:55], v[72:75]
	ds_read_b128 v[120:123], v119 offset:12288
	s_waitcnt lgkmcnt(0)
	v_mfma_f32_16x16x32_bf16 v[76:79], v[120:123], v[52:55], v[76:79]
	ds_read_b128 v[120:123], v119 offset:16384
	s_waitcnt lgkmcnt(0)
	v_mfma_f32_16x16x32_bf16 v[80:83], v[120:123], v[52:55], v[80:83]
	ds_read_b128 v[120:123], v119 offset:20480
	s_waitcnt lgkmcnt(0)
	v_mfma_f32_16x16x32_bf16 v[84:87], v[120:123], v[52:55], v[84:87]
	ds_read_b128 v[120:123], v119 offset:24576
	s_waitcnt lgkmcnt(0)
	v_mfma_f32_16x16x32_bf16 v[88:91], v[120:123], v[52:55], v[88:91]
	ds_read_b128 v[120:123], v119 offset:28672
	v_add_u32_e32 v119, v172, v179
	s_waitcnt lgkmcnt(0)
	v_mfma_f32_16x16x32_bf16 v[92:95], v[120:123], v[52:55], v[92:95]
	ds_read_b128 v[120:123], v119
	s_waitcnt lgkmcnt(0)
	v_mfma_f32_16x16x32_bf16 v[64:67], v[120:123], v[48:51], v[64:67]
	ds_read_b128 v[120:123], v119 offset:4096
	s_waitcnt lgkmcnt(0)
	v_mfma_f32_16x16x32_bf16 v[68:71], v[120:123], v[48:51], v[68:71]
	ds_read_b128 v[120:123], v119 offset:8192
	s_waitcnt lgkmcnt(0)
	v_mfma_f32_16x16x32_bf16 v[72:75], v[120:123], v[48:51], v[72:75]
	ds_read_b128 v[120:123], v119 offset:12288
	s_waitcnt lgkmcnt(0)
	v_mfma_f32_16x16x32_bf16 v[76:79], v[120:123], v[48:51], v[76:79]
	ds_read_b128 v[120:123], v119 offset:16384
	s_waitcnt lgkmcnt(0)
	v_mfma_f32_16x16x32_bf16 v[80:83], v[120:123], v[48:51], v[80:83]
	ds_read_b128 v[120:123], v119 offset:20480
	s_waitcnt lgkmcnt(0)
	v_mfma_f32_16x16x32_bf16 v[84:87], v[120:123], v[48:51], v[84:87]
	ds_read_b128 v[120:123], v119 offset:24576
	s_waitcnt lgkmcnt(0)
	v_mfma_f32_16x16x32_bf16 v[88:91], v[120:123], v[48:51], v[88:91]
	ds_read_b128 v[120:123], v119 offset:28672
	s_waitcnt vmcnt(3)
	ds_write_b128 v115, v[0:3]
	s_waitcnt vmcnt(2)
	ds_write_b128 v221, v[4:7]
	s_waitcnt vmcnt(1)
	ds_write_b128 v222, v[8:11]
	s_waitcnt vmcnt(0)
	ds_write_b128 v223, v[12:15]
	v_add_u32_e32 v12, s24, v165
	v_or_b32_e32 v118, v12, v164
	v_ashrrev_i32_e32 v119, 31, v118
	s_waitcnt lgkmcnt(4)
	v_mfma_f32_16x16x32_bf16 v[92:95], v[120:123], v[48:51], v[92:95]
	v_lshlrev_b64 v[0:1], 13, v[118:119]
	v_or_b32_e32 v122, v12, v174
	v_lshl_add_u64 v[0:1], s[88:89], 0, v[0:1]
	v_ashrrev_i32_e32 v123, 31, v122
	v_lshl_add_u64 v[0:1], v[0:1], 0, s[78:79]
	v_mov_b32_e32 v115, v99
	v_lshlrev_b64 v[4:5], 13, v[122:123]
	v_or_b32_e32 v124, v12, v176
	v_lshl_add_u64 v[0:1], v[0:1], 0, v[114:115]
	v_lshl_add_u64 v[4:5], s[88:89], 0, v[4:5]
	v_ashrrev_i32_e32 v125, 31, v124
	v_add_co_u32_e32 v0, vcc, s33, v0
	v_lshl_add_u64 v[4:5], v[4:5], 0, s[78:79]
	v_lshlrev_b64 v[8:9], 13, v[124:125]
	v_or_b32_e32 v120, v12, v178
	v_addc_co_u32_e32 v1, vcc, 0, v1, vcc
	v_lshl_add_u64 v[4:5], v[4:5], 0, v[114:115]
	v_lshl_add_u64 v[8:9], s[88:89], 0, v[8:9]
	v_ashrrev_i32_e32 v121, 31, v120
	v_add_co_u32_e32 v4, vcc, s33, v4
	v_lshl_add_u64 v[8:9], v[8:9], 0, s[78:79]
	v_lshlrev_b64 v[12:13], 13, v[120:121]
	v_addc_co_u32_e32 v5, vcc, 0, v5, vcc
	v_lshl_add_u64 v[8:9], v[8:9], 0, v[114:115]
	v_lshl_add_u64 v[12:13], s[88:89], 0, v[12:13]
	v_add_co_u32_e32 v8, vcc, s33, v8
	v_lshl_add_u64 v[12:13], v[12:13], 0, s[78:79]
	s_nop 0
	v_addc_co_u32_e32 v9, vcc, 0, v9, vcc
	v_lshl_add_u64 v[12:13], v[12:13], 0, v[114:115]
	v_add_co_u32_e32 v12, vcc, s33, v12
	global_load_dwordx4 v[0:3], v[0:1], off offset:2048
	s_nop 0
	v_addc_co_u32_e32 v13, vcc, 0, v13, vcc
	global_load_dwordx4 v[4:7], v[4:5], off offset:2048
	s_nop 0
	global_load_dwordx4 v[8:11], v[8:9], off offset:2048
	s_nop 0
	global_load_dwordx4 v[12:15], v[12:13], off offset:2048
	ds_read_b32 v115, v180
	ds_read_b128 v[126:129], v181
	ds_read_b128 v[130:133], v182
	s_waitcnt lgkmcnt(1)
; #define LAS __attribute__((address_space(3)))
; template <int DIR>
; __device__ __forceinline__ void mlstm_dir(const f32x4 (&S)[8], f32x4 (&acc)[8], f32x4 (&hs)[8], LAS bf16_t* Ps, const LAS bf16_t* Vt, const LAS float* fl, int wid, int fr, int fq) {
;     ...
;     for (int n = 0; n < 8; ++n) {
;         const int s4 = n * 16 + fq * 4;
;         const f32x4 cs = *(const LAS f32x4*)(cc + s4), is = *(const LAS f32x4*)(ig + s4);
;         float v[4];
; #pragma unroll
;         for (int jj = 0; jj < 4; ++jj) {
;             const int s = s4 + jj;
;             const bool ok = DIR ? (s >= t) : (s <= t);
;             const float arg = DIR ? (cs[jj] - ct + is[jj]) : (ct - cs[jj] + is[jj]);
;             v[jj] = ok ? S[n][jj] * __expf(arg) : 0.f;
;             rsum += v[jj];
;         }
;         u32x2 w; w.x = pk2(v[0], v[1]); w.y = pk2(v[2], v[3]);
;         *(LAS u32x2*)(Ps + t * LROW + s4) = w;
	v_sub_f32_e32 v126, v115, v126
	s_waitcnt lgkmcnt(0)
	v_add_f32_e32 v126, v130, v126
	v_mul_f32_e32 v126, 0x3fb8aa3b, v126
	v_sub_f32_e32 v128, v115, v128
	v_exp_f32_e32 v126, v126
	v_sub_f32_e32 v127, v115, v127
	v_add_f32_e32 v128, v132, v128
	v_add_f32_e32 v127, v131, v127
	v_mul_f32_e32 v128, 0x3fb8aa3b, v128
	v_sub_f32_e32 v129, v115, v129
	v_mul_f32_e32 v127, 0x3fb8aa3b, v127
	v_exp_f32_e32 v128, v128
	v_add_f32_e32 v129, v133, v129
	v_exp_f32_e32 v127, v127
	v_mul_f32_e32 v129, 0x3fb8aa3b, v129
	v_mul_f32_e32 v126, v44, v126
	v_exp_f32_e32 v129, v129
	v_cndmask_b32_e64 v126, v126, 0, s[8:9]
	v_readlane_b32 s8, v252, 42
	v_mul_f32_e32 v128, v46, v128
	v_readlane_b32 s9, v252, 43
	v_mul_f32_e32 v127, v45, v127
	v_cndmask_b32_e64 v127, 0, v127, s[30:31]
	v_cndmask_b32_e64 v128, v128, 0, s[8:9]
	v_readlane_b32 s8, v252, 44
	v_mul_f32_e32 v129, v47, v129
	v_readlane_b32 s9, v252, 45
	v_add_u32_e32 v130, 0x8000, v126
	v_add_u32_e32 v131, 0x8000, v127
	v_cndmask_b32_e64 v129, v129, 0, s[8:9]
	v_perm_b32 v130, v131, v130, s0
	v_add_u32_e32 v131, 0x8000, v128
	v_add_u32_e32 v132, 0x8000, v129
	v_perm_b32 v131, v132, v131, s0
	ds_write_b64 v183, v[130:131] offset:34816
	ds_read_b128 v[130:133], v184
	ds_read_b128 v[134:137], v185
	v_readlane_b32 s8, v252, 46
	v_readlane_b32 s9, v252, 47
	v_add_f32_e32 v126, 0, v126
	s_waitcnt lgkmcnt(1)
	v_sub_f32_e32 v130, v115, v130
	s_waitcnt lgkmcnt(0)
	v_add_f32_e32 v130, v134, v130
	v_mul_f32_e32 v130, 0x3fb8aa3b, v130
	v_sub_f32_e32 v131, v115, v131
	v_exp_f32_e32 v130, v130
	v_add_f32_e32 v131, v135, v131
	v_mul_f32_e32 v131, 0x3fb8aa3b, v131
	v_sub_f32_e32 v132, v115, v132
	v_exp_f32_e32 v131, v131
	v_add_f32_e32 v132, v136, v132
	v_mul_f32_e32 v132, 0x3fb8aa3b, v132
	v_sub_f32_e32 v133, v115, v133
	v_mul_f32_e32 v130, v40, v130
	v_exp_f32_e32 v132, v132
	v_add_f32_e32 v133, v137, v133
	v_cndmask_b32_e64 v130, v130, 0, s[8:9]
	v_readlane_b32 s8, v252, 48
	v_mul_f32_e32 v133, 0x3fb8aa3b, v133
	v_mul_f32_e32 v131, v41, v131
	v_readlane_b32 s9, v252, 49
	v_exp_f32_e32 v133, v133
	v_mul_f32_e32 v132, v42, v132
	v_cndmask_b32_e64 v131, v131, 0, s[8:9]
	v_readlane_b32 s8, v252, 50
	v_readlane_b32 s9, v252, 51
	v_mul_f32_e32 v133, v43, v133
	v_add_u32_e32 v134, 0x8000, v130
	v_cndmask_b32_e64 v132, v132, 0, s[8:9]
	v_readlane_b32 s8, v252, 52
	v_readlane_b32 s9, v252, 53
	v_add_u32_e32 v135, 0x8000, v131
	v_perm_b32 v134, v135, v134, s0
	v_cndmask_b32_e64 v133, v133, 0, s[8:9]
	v_add_u32_e32 v135, 0x8000, v132
	v_add_u32_e32 v136, 0x8000, v133
	v_perm_b32 v135, v136, v135, s0
	ds_write_b64 v183, v[134:135] offset:34848
	ds_read_b128 v[134:137], v186
	ds_read_b128 v[138:141], v187
	v_readlane_b32 s8, v252, 54
	v_readlane_b32 s9, v252, 55
	v_add_f32_e32 v126, v127, v126
	s_waitcnt lgkmcnt(1)
	v_sub_f32_e32 v134, v115, v134
	s_waitcnt lgkmcnt(0)
	v_add_f32_e32 v134, v138, v134
	v_mul_f32_e32 v134, 0x3fb8aa3b, v134
	v_sub_f32_e32 v135, v115, v135
	v_exp_f32_e32 v134, v134
	v_add_f32_e32 v135, v139, v135
	v_mul_f32_e32 v135, 0x3fb8aa3b, v135
	v_sub_f32_e32 v136, v115, v136
	v_exp_f32_e32 v135, v135
	v_add_f32_e32 v136, v140, v136
	v_mul_f32_e32 v136, 0x3fb8aa3b, v136
	v_mul_f32_e32 v134, v36, v134
	v_exp_f32_e32 v136, v136
	v_cndmask_b32_e64 v134, v134, 0, s[8:9]
	v_readlane_b32 s8, v252, 56
	v_mul_f32_e32 v135, v37, v135
	v_readlane_b32 s9, v252, 57
	v_mul_f32_e32 v136, v38, v136
	v_add_f32_e32 v126, v128, v126
	v_cndmask_b32_e64 v135, v135, 0, s[8:9]
	v_readlane_b32 s8, v252, 58
	v_readlane_b32 s9, v252, 59
	v_add_f32_e32 v126, v129, v126
	v_add_f32_e32 v126, v130, v126
	v_cndmask_b32_e64 v144, v136, 0, s[8:9]
	v_sub_f32_e32 v136, v115, v137
	v_add_f32_e32 v136, v141, v136
	v_mul_f32_e32 v136, 0x3fb8aa3b, v136
	v_exp_f32_e32 v136, v136
	v_readlane_b32 s8, v252, 60
	v_readlane_b32 s9, v252, 61
	v_add_u32_e32 v137, 0x8000, v135
	v_mul_f32_e32 v136, v39, v136
	v_cndmask_b32_e64 v145, v136, 0, s[8:9]
	v_add_u32_e32 v136, 0x8000, v134
	v_perm_b32 v136, v137, v136, s0
	v_add_u32_e32 v137, 0x8000, v144
	v_add_u32_e32 v138, 0x8000, v145
	v_perm_b32 v137, v138, v137, s0
	ds_write_b64 v183, v[136:137] offset:34880
	ds_read_b128 v[136:139], v188
	ds_read_b128 v[140:143], v189
	v_readlane_b32 s8, v252, 62
	v_readlane_b32 s9, v252, 63
	v_add_f32_e32 v126, v131, v126
	s_waitcnt lgkmcnt(1)
	v_sub_f32_e32 v136, v115, v136
	s_waitcnt lgkmcnt(0)
	v_add_f32_e32 v136, v140, v136
	v_mul_f32_e32 v136, 0x3fb8aa3b, v136
	v_exp_f32_e32 v136, v136
	v_add_f32_e32 v126, v132, v126
	v_add_f32_e32 v126, v133, v126
	v_add_f32_e32 v126, v134, v126
	v_mul_f32_e32 v136, v32, v136
	v_cndmask_b32_e64 v146, v136, 0, s[8:9]
	v_sub_f32_e32 v136, v115, v137
	v_add_f32_e32 v136, v141, v136
	v_mul_f32_e32 v136, 0x3fb8aa3b, v136
	v_exp_f32_e32 v136, v136
	v_readlane_b32 s8, v251, 0
	v_readlane_b32 s9, v251, 1
	v_add_f32_e32 v126, v135, v126
	v_mul_f32_e32 v136, v33, v136
	v_cndmask_b32_e64 v147, v136, 0, s[8:9]
	v_sub_f32_e32 v136, v115, v138
	v_add_f32_e32 v136, v142, v136
	v_mul_f32_e32 v136, 0x3fb8aa3b, v136
	v_exp_f32_e32 v136, v136
	v_readlane_b32 s8, v251, 2
	v_readlane_b32 s9, v251, 3
	v_add_u32_e32 v137, 0x8000, v147
	v_mul_f32_e32 v136, v34, v136
	v_cndmask_b32_e64 v148, v136, 0, s[8:9]
	v_sub_f32_e32 v136, v115, v139
	v_add_f32_e32 v136, v143, v136
	v_mul_f32_e32 v136, 0x3fb8aa3b, v136
	v_exp_f32_e32 v136, v136
	v_readlane_b32 s8, v251, 4
	v_readlane_b32 s9, v251, 5
	v_add_f32_e32 v126, v144, v126
	v_mul_f32_e32 v136, v35, v136
	v_cndmask_b32_e64 v149, v136, 0, s[8:9]
	v_add_u32_e32 v136, 0x8000, v146
	v_perm_b32 v136, v137, v136, s0
	v_add_u32_e32 v137, 0x8000, v148
	v_add_u32_e32 v138, 0x8000, v149
	v_perm_b32 v137, v138, v137, s0
	ds_write_b64 v183, v[136:137] offset:34912
	ds_read_b128 v[136:139], v190
	ds_read_b128 v[140:143], v191
	v_readlane_b32 s8, v251, 6
	v_readlane_b32 s9, v251, 7
	v_add_f32_e32 v126, v145, v126
	s_waitcnt lgkmcnt(1)
; #define LAS __attribute__((address_space(3)))
; template <int DIR>
; __device__ __forceinline__ void mlstm_dir(const f32x4 (&S)[8], f32x4 (&acc)[8], f32x4 (&hs)[8], LAS bf16_t* Ps, const LAS bf16_t* Vt, const LAS float* fl, int wid, int fr, int fq) {
;     ...
;     for (int n = 0; n < 8; ++n) {
;         const int s4 = n * 16 + fq * 4;
;         const f32x4 cs = *(const LAS f32x4*)(cc + s4), is = *(const LAS f32x4*)(ig + s4);
;         float v[4];
; #pragma unroll
;         for (int jj = 0; jj < 4; ++jj) {
;             const int s = s4 + jj;
;             const bool ok = DIR ? (s >= t) : (s <= t);
;             const float arg = DIR ? (cs[jj] - ct + is[jj]) : (ct - cs[jj] + is[jj]);
;             v[jj] = ok ? S[n][jj] * __expf(arg) : 0.f;
;             rsum += v[jj];
;         }
;         u32x2 w; w.x = pk2(v[0], v[1]); w.y = pk2(v[2], v[3]);
;         *(LAS u32x2*)(Ps + t * LROW + s4) = w;
;     }
;     rsum += __shfl_xor(rsum, 16); rsum += __shfl_xor(rsum, 32);
;     const float den = rsum + si * nq[DIR * 128 + t], scl = 1.f / fmaxf(fabsf(den), 1.f);
; #pragma unroll
;     for (int n = 0; n < 8; ++n) acc[n] *= si;
	v_sub_f32_e32 v136, v115, v136
	s_waitcnt lgkmcnt(0)
	v_add_f32_e32 v136, v140, v136
	v_mul_f32_e32 v136, 0x3fb8aa3b, v136
	v_exp_f32_e32 v136, v136
	v_add_f32_e32 v126, v146, v126
	v_add_f32_e32 v126, v147, v126
	v_add_f32_e32 v126, v148, v126
	v_mul_f32_e32 v136, v28, v136
	v_cndmask_b32_e64 v239, v136, 0, s[8:9]
	v_sub_f32_e32 v136, v115, v137
	v_add_f32_e32 v136, v141, v136
	v_mul_f32_e32 v136, 0x3fb8aa3b, v136
	v_exp_f32_e32 v136, v136
	v_readlane_b32 s8, v251, 8
	v_readlane_b32 s9, v251, 9
	v_add_f32_e32 v126, v149, v126
	v_mul_f32_e32 v136, v29, v136
	v_cndmask_b32_e64 v240, v136, 0, s[8:9]
	v_sub_f32_e32 v136, v115, v138
	v_add_f32_e32 v136, v142, v136
	v_mul_f32_e32 v136, 0x3fb8aa3b, v136
	v_exp_f32_e32 v136, v136
	v_readlane_b32 s8, v251, 10
	v_readlane_b32 s9, v251, 11
	v_add_u32_e32 v137, 0x8000, v240
	v_mul_f32_e32 v136, v30, v136
	v_cndmask_b32_e64 v241, v136, 0, s[8:9]
	v_sub_f32_e32 v136, v115, v139
	v_add_f32_e32 v136, v143, v136
	v_mul_f32_e32 v136, 0x3fb8aa3b, v136
	v_exp_f32_e32 v136, v136
	v_readlane_b32 s8, v251, 12
	v_readlane_b32 s9, v251, 13
	v_add_f32_e32 v126, v239, v126
	v_mul_f32_e32 v136, v31, v136
	v_cndmask_b32_e64 v242, v136, 0, s[8:9]
	v_add_u32_e32 v136, 0x8000, v239
	v_perm_b32 v136, v137, v136, s0
	v_add_u32_e32 v137, 0x8000, v241
	v_add_u32_e32 v138, 0x8000, v242
	v_perm_b32 v137, v138, v137, s0
	ds_write_b64 v183, v[136:137] offset:34944
	ds_read_b128 v[136:139], v192
	ds_read_b128 v[140:143], v193
	v_readlane_b32 s8, v251, 14
	v_readlane_b32 s9, v251, 15
	v_add_f32_e32 v126, v240, v126
	s_waitcnt lgkmcnt(1)
	v_sub_f32_e32 v136, v115, v136
	s_waitcnt lgkmcnt(0)
	v_add_f32_e32 v136, v140, v136
	v_mul_f32_e32 v136, 0x3fb8aa3b, v136
	v_exp_f32_e32 v136, v136
	v_add_f32_e32 v126, v241, v126
	v_add_f32_e32 v126, v242, v126
	v_add_u32_e32 v239, v199, v173
	v_mul_f32_e32 v136, v24, v136
	v_cndmask_b32_e64 v243, v136, 0, s[8:9]
	v_sub_f32_e32 v136, v115, v137
	v_add_f32_e32 v136, v141, v136
	v_mul_f32_e32 v136, 0x3fb8aa3b, v136
	v_exp_f32_e32 v136, v136
	v_readlane_b32 s8, v251, 16
	v_readlane_b32 s9, v251, 17
	v_add_f32_e32 v126, v243, v126
	v_mul_f32_e32 v136, v25, v136
	v_cndmask_b32_e64 v244, v136, 0, s[8:9]
	v_sub_f32_e32 v136, v115, v138
	v_add_f32_e32 v136, v142, v136
	v_mul_f32_e32 v136, 0x3fb8aa3b, v136
	v_exp_f32_e32 v136, v136
	v_readlane_b32 s8, v251, 18
	v_readlane_b32 s9, v251, 19
	v_add_u32_e32 v137, 0x8000, v244
	v_mul_f32_e32 v136, v26, v136
	v_cndmask_b32_e64 v245, v136, 0, s[8:9]
	v_sub_f32_e32 v136, v115, v139
	v_add_f32_e32 v136, v143, v136
	v_mul_f32_e32 v136, 0x3fb8aa3b, v136
	v_exp_f32_e32 v136, v136
	v_readlane_b32 s8, v251, 20
	v_readlane_b32 s9, v251, 21
	v_add_f32_e32 v126, v244, v126
	v_mul_f32_e32 v136, v27, v136
	v_cndmask_b32_e64 v246, v136, 0, s[8:9]
	v_add_u32_e32 v136, 0x8000, v243
	v_perm_b32 v136, v137, v136, s0
	v_add_u32_e32 v137, 0x8000, v245
	v_add_u32_e32 v138, 0x8000, v246
	v_perm_b32 v137, v138, v137, s0
	ds_write_b64 v183, v[136:137] offset:34976
	ds_read_b128 v[136:139], v194
	ds_read_b128 v[140:143], v195
	v_readlane_b32 s8, v251, 22
	v_readlane_b32 s9, v251, 23
	v_add_f32_e32 v126, v245, v126
	s_waitcnt lgkmcnt(1)
	v_sub_f32_e32 v136, v115, v136
	s_waitcnt lgkmcnt(0)
	v_add_f32_e32 v136, v140, v136
	v_mul_f32_e32 v136, 0x3fb8aa3b, v136
	v_exp_f32_e32 v136, v136
	v_add_f32_e32 v126, v246, v126
	v_mul_f32_e32 v136, v20, v136
	v_cndmask_b32_e64 v247, v136, 0, s[8:9]
	v_sub_f32_e32 v136, v115, v137
	v_add_f32_e32 v136, v141, v136
	v_mul_f32_e32 v136, 0x3fb8aa3b, v136
	v_exp_f32_e32 v136, v136
	v_readlane_b32 s8, v251, 24
	v_readlane_b32 s9, v251, 25
	v_add_f32_e32 v126, v247, v126
	v_mul_f32_e32 v136, v21, v136
	v_cndmask_b32_e64 v248, v136, 0, s[8:9]
	v_sub_f32_e32 v136, v115, v138
	v_add_f32_e32 v136, v142, v136
	v_mul_f32_e32 v136, 0x3fb8aa3b, v136
	v_exp_f32_e32 v136, v136
	v_readlane_b32 s8, v251, 26
	v_readlane_b32 s9, v251, 27
	v_add_u32_e32 v137, 0x8000, v248
	v_mul_f32_e32 v136, v22, v136
	v_cndmask_b32_e64 v249, v136, 0, s[8:9]
	v_sub_f32_e32 v136, v115, v139
	v_add_f32_e32 v136, v143, v136
	v_mul_f32_e32 v136, 0x3fb8aa3b, v136
	v_exp_f32_e32 v136, v136
	v_readlane_b32 s8, v251, 28
	v_readlane_b32 s9, v251, 29
	v_add_f32_e32 v126, v248, v126
	v_mul_f32_e32 v136, v23, v136
	v_cndmask_b32_e64 v250, v136, 0, s[8:9]
	v_add_u32_e32 v136, 0x8000, v247
	v_perm_b32 v136, v137, v136, s0
	v_add_u32_e32 v137, 0x8000, v249
	v_add_u32_e32 v138, 0x8000, v250
	v_perm_b32 v137, v138, v137, s0
	ds_write_b64 v183, v[136:137] offset:35008
	ds_read_b128 v[136:139], v196
	ds_read_b128 v[140:143], v197
	v_readlane_b32 s8, v251, 30
	v_readlane_b32 s9, v251, 31
	v_add_f32_e32 v126, v249, v126
	s_waitcnt lgkmcnt(1)
	v_sub_f32_e32 v136, v115, v136
	s_waitcnt lgkmcnt(0)
	v_add_f32_e32 v136, v140, v136
	v_mul_f32_e32 v136, 0x3fb8aa3b, v136
	v_sub_f32_e32 v137, v115, v137
	v_exp_f32_e32 v136, v136
	v_add_f32_e32 v137, v141, v137
	v_mul_f32_e32 v137, 0x3fb8aa3b, v137
	v_sub_f32_e32 v138, v115, v138
	v_exp_f32_e32 v137, v137
	v_add_f32_e32 v138, v142, v138
	v_mul_f32_e32 v138, 0x3fb8aa3b, v138
	v_sub_f32_e32 v139, v115, v139
	v_mul_f32_e32 v136, v16, v136
	v_exp_f32_e32 v138, v138
	v_add_f32_e32 v139, v143, v139
	v_cndmask_b32_e64 v136, v136, 0, s[8:9]
	v_readlane_b32 s8, v251, 32
	v_mul_f32_e32 v139, 0x3fb8aa3b, v139
	v_mul_f32_e32 v137, v17, v137
	v_readlane_b32 s9, v251, 33
	v_exp_f32_e32 v139, v139
	v_mul_f32_e32 v138, v18, v138
	v_cndmask_b32_e64 v137, v137, 0, s[8:9]
	v_readlane_b32 s8, v251, 34
	v_readlane_b32 s9, v251, 35
	v_add_f32_e32 v126, v250, v126
	v_add_f32_e32 v126, v136, v126
	v_cndmask_b32_e64 v138, v138, 0, s[8:9]
	v_readlane_b32 s8, v251, 36
	v_mul_f32_e32 v139, v19, v139
	v_readlane_b32 s9, v251, 37
	v_add_f32_e32 v126, v137, v126
	v_add_f32_e32 v126, v138, v126
	v_cndmask_b32_e64 v139, v139, 0, s[8:9]
	v_add_f32_e32 v129, v139, v126
	v_add_u32_e32 v126, 0x8000, v136
	v_add_u32_e32 v127, 0x8000, v137
	v_mul_f32_e32 v115, 0x3fb8aa3b, v115
	v_perm_b32 v126, v127, v126, s0
	v_add_u32_e32 v127, 0x8000, v138
	v_add_u32_e32 v128, 0x8000, v139
	v_perm_b32 v127, v128, v127, s0
	v_exp_f32_e32 v128, v115
	v_xor_b32_e32 v115, 16, v220
	v_cmp_lt_i32_e32 vcc, v115, v117
	ds_write_b64 v183, v[126:127] offset:35040
	v_xor_b32_e32 v127, 32, v220
	v_cndmask_b32_e32 v115, v220, v115, vcc
	v_lshlrev_b32_e32 v115, 2, v115
	ds_bpermute_b32 v126, v115, v129
	v_cmp_lt_i32_e32 vcc, v127, v117
	v_pk_mul_f32 v[66:67], v[66:67], v[128:129] op_sel_hi:[1,0]
	v_pk_mul_f32 v[64:65], v[64:65], v[128:129] op_sel_hi:[1,0]
	v_cndmask_b32_e32 v117, v220, v127, vcc
	s_waitcnt lgkmcnt(0)
; #define LAS __attribute__((address_space(3)))
; #define MFMA16(a, b, c) __builtin_amdgcn_mfma_f32_16x16x32_bf16((a), (b), (c), 0, 0, 0)
; #define TR_LD8(img, e, p) (*(const LAS bf16x8*)((const LAS unsigned char*)(img) + tr_piece((e), (p))))
; template <int DIR>
; __device__ __forceinline__ void mlstm_dir(const f32x4 (&S)[8], f32x4 (&acc)[8], f32x4 (&hs)[8], LAS bf16_t* Ps, const LAS bf16_t* Vt, const LAS float* fl, int wid, int fr, int fq) {
;     ...
;     rsum += __shfl_xor(rsum, 16); rsum += __shfl_xor(rsum, 32);
;     const float den = rsum + si * nq[DIR * 128 + t], scl = 1.f / fmaxf(fabsf(den), 1.f);
; #pragma unroll
;     for (int n = 0; n < 8; ++n) acc[n] *= si;
;     asm volatile("s_waitcnt lgkmcnt(0)" ::: "memory");
; #pragma unroll
;     for (int kk = 0; kk < 4; ++kk) {
;         const bf16x8 p = *(const LAS bf16x8*)(Ps + (wid * 16 + fr) * LROW + kk * 32 + fq * 8);
; #pragma unroll
;         for (int n = 0; n < 8; ++n) { const bf16x8 vf = TR_LD8(Vt, n * 16 + fr, kk * 4 + fq); acc[n] = MFMA16(vf, p, acc[n]); }
;     }
; #pragma unroll
;     for (int n = 0; n < 8; ++n) hs[n] += acc[n] * scl;
; __device__ __forceinline__ void mlstm_passC(LAS unsigned char* lds, const bf16_t* Z, const float* G, const float* conv_w, const float* conv_b, const float* b_i, const float* b_f, ...
;     ...
;     __syncthreads();
	v_add_f32_e32 v126, v129, v126
	v_lshlrev_b32_e32 v117, 2, v117
	ds_bpermute_b32 v127, v117, v126
	v_pk_mul_f32 v[70:71], v[70:71], v[128:129] op_sel_hi:[1,0]
	v_pk_mul_f32 v[68:69], v[68:69], v[128:129] op_sel_hi:[1,0]
	v_pk_mul_f32 v[74:75], v[74:75], v[128:129] op_sel_hi:[1,0]
	v_pk_mul_f32 v[72:73], v[72:73], v[128:129] op_sel_hi:[1,0]
	s_waitcnt lgkmcnt(0)
	v_add_f32_e32 v126, v126, v127
	ds_read_b32 v127, v198
	s_waitcnt lgkmcnt(0)
	v_pk_mul_f32 v[78:79], v[78:79], v[128:129] op_sel_hi:[1,0]
	v_pk_mul_f32 v[76:77], v[76:77], v[128:129] op_sel_hi:[1,0]
	v_pk_mul_f32 v[82:83], v[82:83], v[128:129] op_sel_hi:[1,0]
	s_waitcnt lgkmcnt(0)
	v_fmac_f32_e32 v126, v128, v127
	v_pk_mul_f32 v[80:81], v[80:81], v[128:129] op_sel_hi:[1,0]
	v_pk_mul_f32 v[86:87], v[86:87], v[128:129] op_sel_hi:[1,0]
	v_pk_mul_f32 v[84:85], v[84:85], v[128:129] op_sel_hi:[1,0]
	v_pk_mul_f32 v[90:91], v[90:91], v[128:129] op_sel_hi:[1,0]
	v_pk_mul_f32 v[88:89], v[88:89], v[128:129] op_sel_hi:[1,0]
	v_pk_mul_f32 v[94:95], v[94:95], v[128:129] op_sel_hi:[1,0]
	v_pk_mul_f32 v[92:93], v[92:93], v[128:129] op_sel_hi:[1,0]
	ds_read_b128 v[128:131], v98 offset:34816
	ds_read_b128 v[132:135], v224
	s_waitcnt lgkmcnt(0)
	v_mfma_f32_16x16x32_bf16 v[64:67], v[132:135], v[128:131], v[64:67]
	ds_read_b128 v[132:135], v225
	v_max_f32_e64 v126, |v126|, 1.0
	s_waitcnt lgkmcnt(0)
	v_mfma_f32_16x16x32_bf16 v[68:71], v[132:135], v[128:131], v[68:71]
	ds_read_b128 v[132:135], v226
	s_waitcnt lgkmcnt(0)
	v_mfma_f32_16x16x32_bf16 v[72:75], v[132:135], v[128:131], v[72:75]
	ds_read_b128 v[132:135], v227
	s_waitcnt lgkmcnt(0)
	v_mfma_f32_16x16x32_bf16 v[76:79], v[132:135], v[128:131], v[76:79]
	ds_read_b128 v[132:135], v228
	s_waitcnt lgkmcnt(0)
	v_mfma_f32_16x16x32_bf16 v[80:83], v[132:135], v[128:131], v[80:83]
	ds_read_b128 v[132:135], v229
	s_waitcnt lgkmcnt(0)
	v_mfma_f32_16x16x32_bf16 v[84:87], v[132:135], v[128:131], v[84:87]
	ds_read_b128 v[132:135], v230
	s_waitcnt lgkmcnt(0)
	v_mfma_f32_16x16x32_bf16 v[88:91], v[132:135], v[128:131], v[88:91]
	ds_read_b128 v[132:135], v231
	s_waitcnt lgkmcnt(0)
	v_mfma_f32_16x16x32_bf16 v[92:95], v[132:135], v[128:131], v[92:95]
	ds_read_b128 v[128:131], v98 offset:34880
	ds_read_b128 v[132:135], v224 offset:64
	s_waitcnt lgkmcnt(0)
	v_mfma_f32_16x16x32_bf16 v[64:67], v[132:135], v[128:131], v[64:67]
	ds_read_b128 v[132:135], v225 offset:64
	s_waitcnt lgkmcnt(0)
	v_mfma_f32_16x16x32_bf16 v[68:71], v[132:135], v[128:131], v[68:71]
	ds_read_b128 v[132:135], v226 offset:64
	s_waitcnt lgkmcnt(0)
	v_mfma_f32_16x16x32_bf16 v[72:75], v[132:135], v[128:131], v[72:75]
	ds_read_b128 v[132:135], v227 offset:64
	s_waitcnt lgkmcnt(0)
	v_mfma_f32_16x16x32_bf16 v[76:79], v[132:135], v[128:131], v[76:79]
	ds_read_b128 v[132:135], v228 offset:64
	s_waitcnt lgkmcnt(0)
	v_mfma_f32_16x16x32_bf16 v[80:83], v[132:135], v[128:131], v[80:83]
	ds_read_b128 v[132:135], v229 offset:64
	s_waitcnt lgkmcnt(0)
	v_mfma_f32_16x16x32_bf16 v[84:87], v[132:135], v[128:131], v[84:87]
	ds_read_b128 v[132:135], v230 offset:64
	s_waitcnt lgkmcnt(0)
	v_mfma_f32_16x16x32_bf16 v[88:91], v[132:135], v[128:131], v[88:91]
	ds_read_b128 v[132:135], v231 offset:64
	s_waitcnt lgkmcnt(0)
	v_mfma_f32_16x16x32_bf16 v[92:95], v[132:135], v[128:131], v[92:95]
	ds_read_b128 v[128:131], v98 offset:34944
	ds_read_b128 v[132:135], v224 offset:128
	s_waitcnt lgkmcnt(0)
	v_mfma_f32_16x16x32_bf16 v[64:67], v[132:135], v[128:131], v[64:67]
	ds_read_b128 v[132:135], v225 offset:128
	s_waitcnt lgkmcnt(0)
	v_mfma_f32_16x16x32_bf16 v[68:71], v[132:135], v[128:131], v[68:71]
	ds_read_b128 v[132:135], v226 offset:128
	s_waitcnt lgkmcnt(0)
	v_mfma_f32_16x16x32_bf16 v[72:75], v[132:135], v[128:131], v[72:75]
	ds_read_b128 v[132:135], v227 offset:128
	s_waitcnt lgkmcnt(0)
	v_mfma_f32_16x16x32_bf16 v[76:79], v[132:135], v[128:131], v[76:79]
	ds_read_b128 v[132:135], v228 offset:128
	s_waitcnt lgkmcnt(0)
	v_mfma_f32_16x16x32_bf16 v[80:83], v[132:135], v[128:131], v[80:83]
	ds_read_b128 v[132:135], v229 offset:128
	s_waitcnt lgkmcnt(0)
	v_mfma_f32_16x16x32_bf16 v[84:87], v[132:135], v[128:131], v[84:87]
	ds_read_b128 v[132:135], v230 offset:128
	s_waitcnt lgkmcnt(0)
	v_mfma_f32_16x16x32_bf16 v[88:91], v[132:135], v[128:131], v[88:91]
	ds_read_b128 v[132:135], v231 offset:128
	s_waitcnt lgkmcnt(0)
	v_mfma_f32_16x16x32_bf16 v[92:95], v[132:135], v[128:131], v[92:95]
	ds_read_b128 v[128:131], v98 offset:35008
	ds_read_b128 v[132:135], v224 offset:192
	s_waitcnt lgkmcnt(0)
	v_mfma_f32_16x16x32_bf16 v[64:67], v[132:135], v[128:131], v[64:67]
	ds_read_b128 v[132:135], v225 offset:192
	s_waitcnt lgkmcnt(0)
	v_mfma_f32_16x16x32_bf16 v[68:71], v[132:135], v[128:131], v[68:71]
	ds_read_b128 v[132:135], v226 offset:192
	s_waitcnt lgkmcnt(0)
	v_mfma_f32_16x16x32_bf16 v[72:75], v[132:135], v[128:131], v[72:75]
	ds_read_b128 v[132:135], v227 offset:192
	s_waitcnt lgkmcnt(0)
	v_mfma_f32_16x16x32_bf16 v[76:79], v[132:135], v[128:131], v[76:79]
	ds_read_b128 v[132:135], v228 offset:192
	s_waitcnt lgkmcnt(0)
	v_mfma_f32_16x16x32_bf16 v[80:83], v[132:135], v[128:131], v[80:83]
	ds_read_b128 v[132:135], v229 offset:192
	s_waitcnt lgkmcnt(0)
	v_mfma_f32_16x16x32_bf16 v[84:87], v[132:135], v[128:131], v[84:87]
	ds_read_b128 v[132:135], v230 offset:192
	s_waitcnt lgkmcnt(0)
	v_mfma_f32_16x16x32_bf16 v[240:243], v[132:135], v[128:131], v[88:91]
	s_nop 2
	ds_read_b128 v[88:91], v231 offset:192
	s_waitcnt lgkmcnt(0)
	s_waitcnt lgkmcnt(0)
	v_mfma_f32_16x16x32_bf16 v[244:247], v[88:91], v[128:131], v[92:95]
	v_div_scale_f32 v88, s[8:9], v126, v126, 1.0
	v_rcp_f32_e32 v89, v88
	s_barrier
; #define LAS __attribute__((address_space(3)))
; #define MFMA16(a, b, c) __builtin_amdgcn_mfma_f32_16x16x32_bf16((a), (b), (c), 0, 0, 0)
; #define TR_LD8(img, e, p) (*(const LAS bf16x8*)((const LAS unsigned char*)(img) + tr_piece((e), (p))))
; template <int DIR>
; __device__ __forceinline__ void mlstm_dir(const f32x4 (&S)[8], f32x4 (&acc)[8], f32x4 (&hs)[8], LAS bf16_t* Ps, const LAS bf16_t* Vt, const LAS float* fl, int wid, int fr, int fq) {
;     ...
;     const float den = rsum + si * nq[DIR * 128 + t], scl = 1.f / fmaxf(fabsf(den), 1.f);
; #pragma unroll
;     for (int n = 0; n < 8; ++n) acc[n] *= si;
;     asm volatile("s_waitcnt lgkmcnt(0)" ::: "memory");
; #pragma unroll
;     for (int kk = 0; kk < 4; ++kk) {
;         const bf16x8 p = *(const LAS bf16x8*)(Ps + (wid * 16 + fr) * LROW + kk * 32 + fq * 8);
; #pragma unroll
;         for (int n = 0; n < 8; ++n) { const bf16x8 vf = TR_LD8(Vt, n * 16 + fr, kk * 4 + fq); acc[n] = MFMA16(vf, p, acc[n]); }
;     }
; #pragma unroll
;     for (int n = 0; n < 8; ++n) hs[n] += acc[n] * scl;
; __device__ __forceinline__ void mlstm_passC(LAS unsigned char* lds, const bf16_t* Z, const float* G, const float* conv_w, const float* conv_b, const float* b_i, const float* b_f, ...
;     ...
;     f32x4 Xb[8];
; #pragma unroll
;     for (int n = 0; n < 8; ++n) Xb[n] = (f32x4){0.f, 0.f, 0.f, 0.f};
; #pragma unroll
;     for (int kk = 0; kk < 4; ++kk)
; #pragma unroll
;         for (int n = 0; n < 8; ++n) { const bf16x8 b1 = *(const LAS bf16x8*)(CB + (n * 16 + fr) * 256 + (((kk * 4 + fq) ^ fr) << 4)); Xb[n] = MFMA16(b1, qa[kk], Xb[n]); }
	v_readlane_b32 s8, v251, 38
	v_fma_f32 v90, -v88, v89, 1.0
	v_fmac_f32_e32 v89, v90, v89
	v_div_scale_f32 v90, vcc, 1.0, v126, 1.0
	v_mul_f32_e32 v91, v90, v89
	v_fma_f32 v92, -v88, v91, v90
	v_fmac_f32_e32 v91, v92, v89
	v_fma_f32 v88, -v88, v91, v90
	v_div_fmas_f32 v88, v88, v89, v91
	v_div_fixup_f32 v92, v88, v126, 1.0
	v_pk_fma_f32 v[144:145], v[92:93], v[64:65], 0 op_sel_hi:[0,1,0]
	v_pk_fma_f32 v[148:149], v[92:93], v[66:67], 0 op_sel_hi:[0,1,0]
	v_pk_fma_f32 v[140:141], v[92:93], v[68:69], 0 op_sel_hi:[0,1,0]
	v_pk_fma_f32 v[146:147], v[92:93], v[70:71], 0 op_sel_hi:[0,1,0]
	v_pk_fma_f32 v[136:137], v[92:93], v[72:73], 0 op_sel_hi:[0,1,0]
	v_pk_fma_f32 v[142:143], v[92:93], v[74:75], 0 op_sel_hi:[0,1,0]
	v_pk_fma_f32 v[132:133], v[92:93], v[76:77], 0 op_sel_hi:[0,1,0]
	v_pk_fma_f32 v[138:139], v[92:93], v[78:79], 0 op_sel_hi:[0,1,0]
	v_pk_fma_f32 v[128:129], v[92:93], v[80:81], 0 op_sel_hi:[0,1,0]
	v_pk_fma_f32 v[134:135], v[92:93], v[82:83], 0 op_sel_hi:[0,1,0]
	v_pk_fma_f32 v[94:95], v[92:93], v[84:85], 0 op_sel_hi:[0,1,0]
	v_pk_fma_f32 v[130:131], v[92:93], v[86:87], 0 op_sel_hi:[0,1,0]
	v_pk_fma_f32 v[90:91], v[92:93], v[240:241], 0 op_sel_hi:[0,1,0]
	v_pk_fma_f32 v[126:127], v[92:93], v[242:243], 0 op_sel_hi:[0,1,0]
	v_pk_fma_f32 v[88:89], v[92:93], v[244:245], 0 op_sel_hi:[0,1,0]
	v_pk_fma_f32 v[92:93], v[92:93], v[246:247], 0 op_sel_hi:[0,1,0]
	ds_read_b128 v[64:67], v239
	ds_read_b128 v[68:71], v239 offset:4096
	ds_read_b128 v[72:75], v239 offset:8192
	ds_read_b128 v[76:79], v239 offset:12288
	ds_read_b128 v[80:83], v239 offset:16384
	ds_read_b128 v[84:87], v239 offset:20480
	ds_read_b128 v[240:243], v239 offset:24576
	ds_read_b128 v[244:247], v239 offset:28672
	v_add_u32_e32 v239, v199, v175
	s_waitcnt lgkmcnt(7)
	v_mfma_f32_16x16x32_bf16 v[64:67], v[64:67], v[60:63], 0
	v_readlane_b32 s9, v251, 39
	s_waitcnt lgkmcnt(6)
	v_mfma_f32_16x16x32_bf16 v[68:71], v[68:71], v[60:63], 0
	s_waitcnt lgkmcnt(5)
	v_mfma_f32_16x16x32_bf16 v[72:75], v[72:75], v[60:63], 0
	s_waitcnt lgkmcnt(4)
	v_mfma_f32_16x16x32_bf16 v[76:79], v[76:79], v[60:63], 0
	s_waitcnt lgkmcnt(3)
	v_mfma_f32_16x16x32_bf16 v[80:83], v[80:83], v[60:63], 0
	s_waitcnt lgkmcnt(2)
	v_mfma_f32_16x16x32_bf16 v[84:87], v[84:87], v[60:63], 0
	s_waitcnt lgkmcnt(1)
	v_mfma_f32_16x16x32_bf16 v[240:243], v[240:243], v[60:63], 0
	s_waitcnt lgkmcnt(0)
	v_mfma_f32_16x16x32_bf16 v[60:63], v[244:247], v[60:63], 0
	ds_read_b128 v[244:247], v239
	s_waitcnt lgkmcnt(0)
	v_mfma_f32_16x16x32_bf16 v[64:67], v[244:247], v[56:59], v[64:67]
	ds_read_b128 v[244:247], v239 offset:4096
	s_waitcnt lgkmcnt(0)
	v_mfma_f32_16x16x32_bf16 v[68:71], v[244:247], v[56:59], v[68:71]
	ds_read_b128 v[244:247], v239 offset:8192
	s_waitcnt lgkmcnt(0)
	v_mfma_f32_16x16x32_bf16 v[72:75], v[244:247], v[56:59], v[72:75]
	ds_read_b128 v[244:247], v239 offset:12288
	s_waitcnt lgkmcnt(0)
	v_mfma_f32_16x16x32_bf16 v[76:79], v[244:247], v[56:59], v[76:79]
	ds_read_b128 v[244:247], v239 offset:16384
	s_waitcnt lgkmcnt(0)
	v_mfma_f32_16x16x32_bf16 v[80:83], v[244:247], v[56:59], v[80:83]
	ds_read_b128 v[244:247], v239 offset:20480
	s_waitcnt lgkmcnt(0)
	v_mfma_f32_16x16x32_bf16 v[84:87], v[244:247], v[56:59], v[84:87]
	ds_read_b128 v[244:247], v239 offset:24576
	s_waitcnt lgkmcnt(0)
	v_mfma_f32_16x16x32_bf16 v[240:243], v[244:247], v[56:59], v[240:243]
	ds_read_b128 v[244:247], v239 offset:28672
	v_add_u32_e32 v239, v199, v177
	s_waitcnt lgkmcnt(0)
	v_mfma_f32_16x16x32_bf16 v[56:59], v[244:247], v[56:59], v[60:63]
	s_nop 2
	ds_read_b128 v[60:63], v239
	s_waitcnt lgkmcnt(0)
	v_mfma_f32_16x16x32_bf16 v[60:63], v[60:63], v[52:55], v[64:67]
	s_nop 2
	ds_read_b128 v[64:67], v239 offset:4096
	s_waitcnt lgkmcnt(0)
	v_mfma_f32_16x16x32_bf16 v[64:67], v[64:67], v[52:55], v[68:71]
	s_nop 2
	ds_read_b128 v[68:71], v239 offset:8192
	s_waitcnt lgkmcnt(0)
	v_mfma_f32_16x16x32_bf16 v[68:71], v[68:71], v[52:55], v[72:75]
	s_nop 2
	ds_read_b128 v[72:75], v239 offset:12288
	s_waitcnt lgkmcnt(0)
	v_mfma_f32_16x16x32_bf16 v[72:75], v[72:75], v[52:55], v[76:79]
	s_nop 2
	ds_read_b128 v[76:79], v239 offset:16384
	s_waitcnt lgkmcnt(0)
	v_mfma_f32_16x16x32_bf16 v[76:79], v[76:79], v[52:55], v[80:83]
	s_nop 2
	ds_read_b128 v[80:83], v239 offset:20480
	s_waitcnt lgkmcnt(0)
	v_mfma_f32_16x16x32_bf16 v[80:83], v[80:83], v[52:55], v[84:87]
	s_nop 2
	ds_read_b128 v[84:87], v239 offset:24576
	s_waitcnt lgkmcnt(0)
	v_mfma_f32_16x16x32_bf16 v[84:87], v[84:87], v[52:55], v[240:243]
	s_nop 2
	ds_read_b128 v[240:243], v239 offset:28672
	v_add_u32_e32 v239, v199, v179
	s_waitcnt lgkmcnt(0)
	v_mfma_f32_16x16x32_bf16 v[240:243], v[240:243], v[52:55], v[56:59]
	ds_read_b128 v[52:55], v239
	s_nop 1
	ds_read_b128 v[56:59], v239 offset:4096
	s_waitcnt lgkmcnt(1)
	v_mfma_f32_16x16x32_bf16 v[52:55], v[52:55], v[48:51], v[60:63]
	s_nop 2
	ds_read_b128 v[60:63], v239 offset:8192
	s_waitcnt lgkmcnt(1)
	v_mfma_f32_16x16x32_bf16 v[56:59], v[56:59], v[48:51], v[64:67]
	s_nop 2
	ds_read_b128 v[64:67], v239 offset:12288
	s_waitcnt lgkmcnt(1)
	v_mfma_f32_16x16x32_bf16 v[60:63], v[60:63], v[48:51], v[68:71]
	s_nop 2
	ds_read_b128 v[68:71], v239 offset:16384
	s_waitcnt lgkmcnt(1)
	v_mfma_f32_16x16x32_bf16 v[64:67], v[64:67], v[48:51], v[72:75]
	s_nop 2
	ds_read_b128 v[72:75], v239 offset:20480
	s_waitcnt lgkmcnt(1)
	v_mfma_f32_16x16x32_bf16 v[68:71], v[68:71], v[48:51], v[76:79]
	s_nop 2
	ds_read_b128 v[76:79], v239 offset:24576
	s_waitcnt lgkmcnt(1)
	v_mfma_f32_16x16x32_bf16 v[72:75], v[72:75], v[48:51], v[80:83]
	s_nop 2
	ds_read_b128 v[80:83], v239 offset:28672
	s_waitcnt lgkmcnt(1)
	v_mfma_f32_16x16x32_bf16 v[76:79], v[76:79], v[48:51], v[84:87]
	ds_read_b32 v239, v200
	s_waitcnt lgkmcnt(1)
; #define LAS __attribute__((address_space(3)))
; template <int DIR>
; __device__ __forceinline__ void mlstm_dir(const f32x4 (&S)[8], f32x4 (&acc)[8], f32x4 (&hs)[8], LAS bf16_t* Ps, const LAS bf16_t* Vt, const LAS float* fl, int wid, int fr, int fq) {
;     const LAS float* ig = fl + (DIR ? 384 : 256); const LAS float* cc = fl + (DIR ? 640 : 512); const LAS float* tot = fl + 768; const LAS float* nq = fl + 1152;
;     const int t = wid * 16 + fr;
;     const float ct = cc[t], si = DIR ? __expf(tot[1] - ct) : __expf(ct);
;     float rsum = 0.f;
; #pragma unroll
;     for (int n = 0; n < 8; ++n) {
;         const int s4 = n * 16 + fq * 4;
;         const f32x4 cs = *(const LAS f32x4*)(cc + s4), is = *(const LAS f32x4*)(ig + s4);
;         float v[4];
; #pragma unroll
;         for (int jj = 0; jj < 4; ++jj) {
;             const int s = s4 + jj;
;             const bool ok = DIR ? (s >= t) : (s <= t);
;             const float arg = DIR ? (cs[jj] - ct + is[jj]) : (ct - cs[jj] + is[jj]);
;             v[jj] = ok ? S[n][jj] * __expf(arg) : 0.f;
;             rsum += v[jj];
;         }
;         u32x2 w; w.x = pk2(v[0], v[1]); w.y = pk2(v[2], v[3]);
;         *(LAS u32x2*)(Ps + t * LROW + s4) = w;
	v_mfma_f32_16x16x32_bf16 v[48:51], v[80:83], v[48:51], v[240:243]
	v_mov_b32_e32 v80, s1
	s_nop 1
	ds_read_b32 v240, v80
	ds_read_b128 v[80:83], v201
	ds_read_b128 v[84:87], v202
	s_waitcnt lgkmcnt(1)
	v_sub_f32_e32 v80, v80, v239
	s_waitcnt lgkmcnt(0)
	v_add_f32_e32 v80, v84, v80
	v_mul_f32_e32 v80, 0x3fb8aa3b, v80
	v_exp_f32_e32 v80, v80
	s_nop 0
	v_mul_f32_e32 v44, v44, v80
	v_sub_f32_e32 v80, v81, v239
	v_add_f32_e32 v80, v85, v80
	v_mul_f32_e32 v80, 0x3fb8aa3b, v80
	v_exp_f32_e32 v80, v80
	v_cndmask_b32_e64 v44, v44, 0, s[30:31]
	v_mul_f32_e32 v45, v45, v80
	v_sub_f32_e32 v80, v82, v239
	v_add_f32_e32 v80, v86, v80
	v_mul_f32_e32 v80, 0x3fb8aa3b, v80
	v_exp_f32_e32 v80, v80
	v_cndmask_b32_e64 v45, v45, 0, s[8:9]
	v_readlane_b32 s8, v251, 40
	v_readlane_b32 s9, v251, 41
	v_mul_f32_e32 v46, v46, v80
	v_sub_f32_e32 v80, v83, v239
	v_add_f32_e32 v80, v87, v80
	v_mul_f32_e32 v80, 0x3fb8aa3b, v80
	v_exp_f32_e32 v80, v80
	v_cndmask_b32_e64 v46, v46, 0, s[8:9]
	v_readlane_b32 s8, v251, 42
	v_readlane_b32 s9, v251, 43
	v_mul_f32_e32 v47, v47, v80
	v_add_u32_e32 v80, 0x8000, v44
	v_cndmask_b32_e64 v47, v47, 0, s[8:9]
	v_add_u32_e32 v81, 0x8000, v45
	v_perm_b32 v80, v81, v80, s0
	v_add_u32_e32 v81, 0x8000, v46
	v_add_u32_e32 v82, 0x8000, v47
	v_perm_b32 v81, v82, v81, s0
	ds_write_b64 v183, v[80:81] offset:34816
	ds_read_b128 v[80:83], v203
	ds_read_b128 v[84:87], v204
	v_readlane_b32 s8, v251, 44
	v_readlane_b32 s9, v251, 45
	s_waitcnt lgkmcnt(1)
	v_sub_f32_e32 v80, v80, v239
	s_waitcnt lgkmcnt(0)
	v_add_f32_e32 v80, v84, v80
	v_mul_f32_e32 v80, 0x3fb8aa3b, v80
	v_exp_f32_e32 v80, v80
	s_nop 0
	v_mul_f32_e32 v40, v40, v80
	v_cndmask_b32_e64 v80, v40, 0, s[8:9]
	v_sub_f32_e32 v40, v81, v239
	v_add_f32_e32 v40, v85, v40
	v_mul_f32_e32 v40, 0x3fb8aa3b, v40
	v_exp_f32_e32 v40, v40
	v_readlane_b32 s8, v251, 46
	v_readlane_b32 s9, v251, 47
	v_mul_f32_e32 v40, v41, v40
	s_nop 0
	v_cndmask_b32_e64 v81, v40, 0, s[8:9]
	v_sub_f32_e32 v40, v82, v239
	v_add_f32_e32 v40, v86, v40
	v_mul_f32_e32 v40, 0x3fb8aa3b, v40
	v_exp_f32_e32 v40, v40
	v_readlane_b32 s8, v251, 48
	v_readlane_b32 s9, v251, 49
	v_add_u32_e32 v41, 0x8000, v81
	v_mul_f32_e32 v40, v42, v40
	v_cndmask_b32_e64 v82, v40, 0, s[8:9]
	v_sub_f32_e32 v40, v83, v239
	v_add_f32_e32 v40, v87, v40
	v_mul_f32_e32 v40, 0x3fb8aa3b, v40
	v_exp_f32_e32 v40, v40
	v_readlane_b32 s8, v251, 50
	v_readlane_b32 s9, v251, 51
	v_mul_f32_e32 v40, v43, v40
	s_nop 0
	v_cndmask_b32_e64 v83, v40, 0, s[8:9]
	v_add_u32_e32 v40, 0x8000, v80
	v_perm_b32 v40, v41, v40, s0
	v_add_u32_e32 v41, 0x8000, v82
	v_add_u32_e32 v42, 0x8000, v83
	v_perm_b32 v41, v42, v41, s0
	ds_write_b64 v183, v[40:41] offset:34848
	ds_read_b128 v[84:87], v205
	ds_read_b128 v[40:43], v206
	v_readlane_b32 s8, v251, 52
	v_readlane_b32 s9, v251, 53
	s_waitcnt lgkmcnt(1)
	v_sub_f32_e32 v84, v84, v239
	s_waitcnt lgkmcnt(0)
	v_add_f32_e32 v40, v40, v84
	v_mul_f32_e32 v40, 0x3fb8aa3b, v40
	v_exp_f32_e32 v40, v40
	s_nop 0
	v_mul_f32_e32 v36, v36, v40
	v_sub_f32_e32 v40, v85, v239
	v_add_f32_e32 v40, v41, v40
	v_mul_f32_e32 v40, 0x3fb8aa3b, v40
	v_exp_f32_e32 v40, v40
	v_cndmask_b32_e64 v36, v36, 0, s[8:9]
	v_readlane_b32 s8, v251, 54
	v_readlane_b32 s9, v251, 55
	v_mul_f32_e32 v37, v37, v40
	v_sub_f32_e32 v40, v86, v239
	v_add_f32_e32 v40, v42, v40
	v_mul_f32_e32 v40, 0x3fb8aa3b, v40
	v_exp_f32_e32 v40, v40
	v_cndmask_b32_e64 v37, v37, 0, s[8:9]
	v_add_u32_e32 v41, 0x8000, v37
	v_mul_f32_e32 v38, v38, v40
	v_sub_f32_e32 v40, v87, v239
	v_add_f32_e32 v40, v43, v40
	v_mul_f32_e32 v40, 0x3fb8aa3b, v40
	v_exp_f32_e32 v40, v40
	v_cndmask_b32_e64 v38, v38, 0, s[14:15]
	v_mul_f32_e32 v39, v39, v40
	v_cndmask_b32_e64 v39, v39, 0, s[16:17]
	v_add_u32_e32 v40, 0x8000, v36
	v_perm_b32 v40, v41, v40, s0
	v_add_u32_e32 v41, 0x8000, v38
	v_add_u32_e32 v42, 0x8000, v39
	v_perm_b32 v41, v42, v41, s0
	ds_write_b64 v183, v[40:41] offset:34880
	ds_read_b128 v[40:43], v207
	ds_read_b128 v[84:87], v208
	s_waitcnt lgkmcnt(1)
	v_sub_f32_e32 v40, v40, v239
	s_waitcnt lgkmcnt(0)
	v_add_f32_e32 v40, v84, v40
	v_mul_f32_e32 v40, 0x3fb8aa3b, v40
	v_exp_f32_e32 v40, v40
	s_nop 0
	v_mul_f32_e32 v32, v32, v40
	v_sub_f32_e32 v40, v41, v239
	v_add_f32_e32 v40, v85, v40
	v_mul_f32_e32 v40, 0x3fb8aa3b, v40
	v_exp_f32_e32 v40, v40
	v_cndmask_b32_e64 v32, v32, 0, s[18:19]
	v_mul_f32_e32 v33, v33, v40
	v_sub_f32_e32 v40, v42, v239
	v_add_f32_e32 v40, v86, v40
	v_mul_f32_e32 v40, 0x3fb8aa3b, v40
	v_exp_f32_e32 v40, v40
	v_cndmask_b32_e64 v33, v33, 0, s[22:23]
	v_add_u32_e32 v41, 0x8000, v33
	v_mul_f32_e32 v34, v34, v40
	v_sub_f32_e32 v40, v43, v239
	v_add_f32_e32 v40, v87, v40
	v_mul_f32_e32 v40, 0x3fb8aa3b, v40
	v_exp_f32_e32 v40, v40
	v_cndmask_b32_e64 v34, v34, 0, s[26:27]
	v_mul_f32_e32 v35, v35, v40
	v_cndmask_b32_e64 v35, v35, 0, s[28:29]
	v_add_u32_e32 v40, 0x8000, v32
	v_perm_b32 v40, v41, v40, s0
	v_add_u32_e32 v41, 0x8000, v34
	v_add_u32_e32 v42, 0x8000, v35
	v_perm_b32 v41, v42, v41, s0
	ds_write_b64 v183, v[40:41] offset:34912
	ds_read_b128 v[40:43], v209
	ds_read_b128 v[84:87], v210
	s_waitcnt lgkmcnt(1)
	v_sub_f32_e32 v40, v40, v239
	s_waitcnt lgkmcnt(0)
	v_add_f32_e32 v40, v84, v40
	v_mul_f32_e32 v40, 0x3fb8aa3b, v40
	v_exp_f32_e32 v40, v40
	s_nop 0
	v_mul_f32_e32 v28, v28, v40
	v_cndmask_b32_e64 v84, v28, 0, s[34:35]
	v_sub_f32_e32 v28, v41, v239
	v_add_f32_e32 v28, v85, v28
	v_mul_f32_e32 v28, 0x3fb8aa3b, v28
	v_exp_f32_e32 v28, v28
	s_nop 0
	v_mul_f32_e32 v28, v29, v28
	v_cndmask_b32_e64 v85, v28, 0, s[36:37]
	v_sub_f32_e32 v28, v42, v239
	v_add_f32_e32 v28, v86, v28
	v_mul_f32_e32 v28, 0x3fb8aa3b, v28
	v_exp_f32_e32 v28, v28
	v_add_u32_e32 v29, 0x8000, v85
	v_mul_f32_e32 v28, v30, v28
	v_cndmask_b32_e64 v86, v28, 0, s[38:39]
	v_sub_f32_e32 v28, v43, v239
	v_add_f32_e32 v28, v87, v28
	v_mul_f32_e32 v28, 0x3fb8aa3b, v28
	v_exp_f32_e32 v28, v28
	s_nop 0
	v_mul_f32_e32 v28, v31, v28
	v_cndmask_b32_e64 v87, v28, 0, s[40:41]
	v_add_u32_e32 v28, 0x8000, v84
	v_perm_b32 v28, v29, v28, s0
	v_add_u32_e32 v29, 0x8000, v86
	v_add_u32_e32 v30, 0x8000, v87
	v_perm_b32 v29, v30, v29, s0
	ds_write_b64 v183, v[28:29] offset:34944
	ds_read_b128 v[28:31], v211
	ds_read_b128 v[40:43], v212
	s_waitcnt lgkmcnt(1)
; #define LAS __attribute__((address_space(3)))
; #define MFMA16(a, b, c) __builtin_amdgcn_mfma_f32_16x16x32_bf16((a), (b), (c), 0, 0, 0)
; #define TR_LD8(img, e, p) (*(const LAS bf16x8*)((const LAS unsigned char*)(img) + tr_piece((e), (p))))
; template <int DIR>
; __device__ __forceinline__ void mlstm_dir(const f32x4 (&S)[8], f32x4 (&acc)[8], f32x4 (&hs)[8], LAS bf16_t* Ps, const LAS bf16_t* Vt, const LAS float* fl, int wid, int fr, int fq) {
;     ...
;     const float ct = cc[t], si = DIR ? __expf(tot[1] - ct) : __expf(ct);
;     float rsum = 0.f;
; #pragma unroll
;     for (int n = 0; n < 8; ++n) {
;         const int s4 = n * 16 + fq * 4;
;         const f32x4 cs = *(const LAS f32x4*)(cc + s4), is = *(const LAS f32x4*)(ig + s4);
;         float v[4];
; #pragma unroll
;         for (int jj = 0; jj < 4; ++jj) {
;             const int s = s4 + jj;
;             const bool ok = DIR ? (s >= t) : (s <= t);
;             const float arg = DIR ? (cs[jj] - ct + is[jj]) : (ct - cs[jj] + is[jj]);
;             v[jj] = ok ? S[n][jj] * __expf(arg) : 0.f;
;             rsum += v[jj];
;         }
;         u32x2 w; w.x = pk2(v[0], v[1]); w.y = pk2(v[2], v[3]);
;         *(LAS u32x2*)(Ps + t * LROW + s4) = w;
;     }
;     rsum += __shfl_xor(rsum, 16); rsum += __shfl_xor(rsum, 32);
;     const float den = rsum + si * nq[DIR * 128 + t], scl = 1.f / fmaxf(fabsf(den), 1.f);
; #pragma unroll
;     for (int n = 0; n < 8; ++n) acc[n] *= si;
;     asm volatile("s_waitcnt lgkmcnt(0)" ::: "memory");
; #pragma unroll
;     for (int kk = 0; kk < 4; ++kk) {
;         const bf16x8 p = *(const LAS bf16x8*)(Ps + (wid * 16 + fr) * LROW + kk * 32 + fq * 8);
; #pragma unroll
;         for (int n = 0; n < 8; ++n) { const bf16x8 vf = TR_LD8(Vt, n * 16 + fr, kk * 4 + fq); acc[n] = MFMA16(vf, p, acc[n]); }
	v_sub_f32_e32 v28, v28, v239
	s_waitcnt lgkmcnt(0)
	v_add_f32_e32 v28, v40, v28
	v_mul_f32_e32 v28, 0x3fb8aa3b, v28
	v_exp_f32_e32 v28, v28
	s_nop 0
	v_mul_f32_e32 v24, v24, v28
	v_cndmask_b32_e64 v40, v24, 0, s[42:43]
	v_sub_f32_e32 v24, v29, v239
	v_add_f32_e32 v24, v41, v24
	v_mul_f32_e32 v24, 0x3fb8aa3b, v24
	v_exp_f32_e32 v24, v24
	s_nop 0
	v_mul_f32_e32 v24, v25, v24
	v_cndmask_b32_e64 v41, v24, 0, s[44:45]
	v_sub_f32_e32 v24, v30, v239
	v_add_f32_e32 v24, v42, v24
	v_mul_f32_e32 v24, 0x3fb8aa3b, v24
	v_exp_f32_e32 v24, v24
	v_add_u32_e32 v25, 0x8000, v41
	v_mul_f32_e32 v24, v26, v24
	v_cndmask_b32_e64 v42, v24, 0, s[46:47]
	v_sub_f32_e32 v24, v31, v239
	v_add_f32_e32 v24, v43, v24
	v_mul_f32_e32 v24, 0x3fb8aa3b, v24
	v_exp_f32_e32 v24, v24
	s_nop 0
	v_mul_f32_e32 v24, v27, v24
	v_cndmask_b32_e64 v43, v24, 0, s[48:49]
	v_add_u32_e32 v24, 0x8000, v40
	v_perm_b32 v24, v25, v24, s0
	v_add_u32_e32 v25, 0x8000, v42
	v_add_u32_e32 v26, 0x8000, v43
	v_perm_b32 v25, v26, v25, s0
	ds_write_b64 v183, v[24:25] offset:34976
	ds_read_b128 v[24:27], v213
	ds_read_b128 v[28:31], v214
	s_waitcnt lgkmcnt(1)
	v_sub_f32_e32 v24, v24, v239
	s_waitcnt lgkmcnt(0)
	v_add_f32_e32 v24, v28, v24
	v_mul_f32_e32 v24, 0x3fb8aa3b, v24
	v_exp_f32_e32 v24, v24
	s_nop 0
	v_mul_f32_e32 v20, v20, v24
	v_cndmask_b32_e64 v28, v20, 0, s[50:51]
	v_sub_f32_e32 v20, v25, v239
	v_add_f32_e32 v20, v29, v20
	v_mul_f32_e32 v20, 0x3fb8aa3b, v20
	v_exp_f32_e32 v20, v20
	s_nop 0
	v_mul_f32_e32 v20, v21, v20
	v_cndmask_b32_e64 v29, v20, 0, s[52:53]
	v_sub_f32_e32 v20, v26, v239
	v_add_f32_e32 v20, v30, v20
	v_mul_f32_e32 v20, 0x3fb8aa3b, v20
	v_exp_f32_e32 v20, v20
	v_add_u32_e32 v21, 0x8000, v29
	v_mul_f32_e32 v20, v22, v20
	v_cndmask_b32_e64 v30, v20, 0, s[54:55]
	v_sub_f32_e32 v20, v27, v239
	v_add_f32_e32 v20, v31, v20
	v_mul_f32_e32 v20, 0x3fb8aa3b, v20
	v_exp_f32_e32 v20, v20
	s_nop 0
	v_mul_f32_e32 v20, v23, v20
	v_cndmask_b32_e64 v31, v20, 0, s[56:57]
	v_add_u32_e32 v20, 0x8000, v28
	v_perm_b32 v20, v21, v20, s0
	v_add_u32_e32 v21, 0x8000, v30
	v_add_u32_e32 v22, 0x8000, v31
	v_perm_b32 v21, v22, v21, s0
	ds_write_b64 v183, v[20:21] offset:35008
	ds_read_b128 v[20:23], v215
	ds_read_b128 v[24:27], v216
	s_waitcnt lgkmcnt(1)
	v_sub_f32_e32 v20, v20, v239
	s_waitcnt lgkmcnt(0)
	v_add_f32_e32 v20, v24, v20
	v_mul_f32_e32 v20, 0x3fb8aa3b, v20
	v_exp_f32_e32 v20, v20
	s_nop 0
	v_mul_f32_e32 v16, v16, v20
	v_sub_f32_e32 v20, v21, v239
	v_add_f32_e32 v20, v25, v20
	v_mul_f32_e32 v20, 0x3fb8aa3b, v20
	v_exp_f32_e32 v20, v20
	v_cndmask_b32_e64 v16, v16, 0, s[58:59]
	v_sub_f32_e32 v21, v240, v239
	v_mul_f32_e32 v21, 0x3fb8aa3b, v21
	v_mul_f32_e32 v17, v17, v20
	v_sub_f32_e32 v20, v22, v239
	v_add_f32_e32 v20, v26, v20
	v_mul_f32_e32 v20, 0x3fb8aa3b, v20
	v_exp_f32_e32 v20, v20
	v_cndmask_b32_e64 v17, v17, 0, s[60:61]
	v_mul_f32_e32 v18, v18, v20
	v_sub_f32_e32 v20, v23, v239
	v_add_f32_e32 v20, v27, v20
	v_mul_f32_e32 v20, 0x3fb8aa3b, v20
	v_exp_f32_e32 v20, v20
	v_cndmask_b32_e64 v18, v18, 0, s[62:63]
	v_mul_f32_e32 v19, v19, v20
	v_add_f32_e32 v20, 0, v44
	v_add_f32_e32 v20, v45, v20
	v_add_f32_e32 v20, v46, v20
	v_add_f32_e32 v20, v47, v20
	v_add_f32_e32 v20, v80, v20
	v_add_f32_e32 v20, v81, v20
	v_add_f32_e32 v20, v82, v20
	v_add_f32_e32 v20, v83, v20
	v_add_f32_e32 v20, v36, v20
	v_add_f32_e32 v20, v37, v20
	v_add_f32_e32 v20, v38, v20
	v_add_f32_e32 v20, v39, v20
	v_add_f32_e32 v20, v32, v20
	v_add_f32_e32 v20, v33, v20
	v_add_f32_e32 v20, v34, v20
	v_add_f32_e32 v20, v35, v20
	v_add_f32_e32 v20, v84, v20
	v_add_f32_e32 v20, v85, v20
	v_add_f32_e32 v20, v86, v20
	v_add_f32_e32 v20, v87, v20
	v_add_f32_e32 v20, v40, v20
	v_add_f32_e32 v20, v41, v20
	v_add_f32_e32 v20, v42, v20
	v_add_f32_e32 v20, v43, v20
	v_add_f32_e32 v20, v28, v20
	v_add_f32_e32 v20, v29, v20
	v_add_f32_e32 v20, v30, v20
	v_add_f32_e32 v20, v31, v20
	v_add_f32_e32 v20, v16, v20
	v_cndmask_b32_e64 v19, v19, 0, s[64:65]
	v_add_f32_e32 v20, v17, v20
	v_add_u32_e32 v16, 0x8000, v16
	v_add_u32_e32 v17, 0x8000, v17
	v_add_f32_e32 v20, v18, v20
	v_perm_b32 v16, v17, v16, s0
	v_add_u32_e32 v17, 0x8000, v18
	v_add_u32_e32 v18, 0x8000, v19
	v_add_f32_e32 v20, v19, v20
	v_perm_b32 v17, v18, v17, s0
	ds_write_b64 v183, v[16:17] offset:35040
	ds_bpermute_b32 v16, v115, v20
	v_exp_f32_e32 v44, v21
	s_waitcnt lgkmcnt(0)
	v_add_f32_e32 v16, v20, v16
	ds_bpermute_b32 v17, v117, v16
	v_pk_mul_f32 v[18:19], v[54:55], v[44:45] op_sel_hi:[1,0]
	v_pk_mul_f32 v[22:23], v[58:59], v[44:45] op_sel_hi:[1,0]
	v_pk_mul_f32 v[20:21], v[56:57], v[44:45] op_sel_hi:[1,0]
	v_pk_mul_f32 v[26:27], v[62:63], v[44:45] op_sel_hi:[1,0]
	s_waitcnt lgkmcnt(0)
	v_add_f32_e32 v16, v16, v17
	ds_read_b32 v17, v198 offset:512
	s_waitcnt lgkmcnt(0)
	v_pk_mul_f32 v[24:25], v[60:61], v[44:45] op_sel_hi:[1,0]
	v_pk_mul_f32 v[30:31], v[66:67], v[44:45] op_sel_hi:[1,0]
	v_pk_mul_f32 v[28:29], v[64:65], v[44:45] op_sel_hi:[1,0]
	s_waitcnt lgkmcnt(0)
	v_fmac_f32_e32 v16, v44, v17
	v_max_f32_e64 v80, |v16|, 1.0
	v_pk_mul_f32 v[16:17], v[52:53], v[44:45] op_sel_hi:[1,0]
	v_pk_mul_f32 v[34:35], v[70:71], v[44:45] op_sel_hi:[1,0]
	v_pk_mul_f32 v[32:33], v[68:69], v[44:45] op_sel_hi:[1,0]
	v_pk_mul_f32 v[38:39], v[74:75], v[44:45] op_sel_hi:[1,0]
	v_pk_mul_f32 v[36:37], v[72:73], v[44:45] op_sel_hi:[1,0]
	v_pk_mul_f32 v[42:43], v[78:79], v[44:45] op_sel_hi:[1,0]
	v_pk_mul_f32 v[40:41], v[76:77], v[44:45] op_sel_hi:[1,0]
	v_pk_mul_f32 v[46:47], v[50:51], v[44:45] op_sel_hi:[1,0]
	v_pk_mul_f32 v[44:45], v[48:49], v[44:45] op_sel_hi:[1,0]
	ds_read_b128 v[48:51], v98 offset:34816
	ds_read_b128 v[52:55], v224
	s_waitcnt lgkmcnt(0)
; #define LAS __attribute__((address_space(3)))
; #define MFMA16(a, b, c) __builtin_amdgcn_mfma_f32_16x16x32_bf16((a), (b), (c), 0, 0, 0)
; #define TR_LD8(img, e, p) (*(const LAS bf16x8*)((const LAS unsigned char*)(img) + tr_piece((e), (p))))
; template <int DIR>
; __device__ __forceinline__ void mlstm_dir(const f32x4 (&S)[8], f32x4 (&acc)[8], f32x4 (&hs)[8], LAS bf16_t* Ps, const LAS bf16_t* Vt, const LAS float* fl, int wid, int fr, int fq) {
;     ...
;     for (int kk = 0; kk < 4; ++kk) {
;         const bf16x8 p = *(const LAS bf16x8*)(Ps + (wid * 16 + fr) * LROW + kk * 32 + fq * 8);
; #pragma unroll
;         for (int n = 0; n < 8; ++n) { const bf16x8 vf = TR_LD8(Vt, n * 16 + fr, kk * 4 + fq); acc[n] = MFMA16(vf, p, acc[n]); }
;     }
; #pragma unroll
; __device__ __forceinline__ void mlstm_passC(LAS unsigned char* lds, const bf16_t* Z, const float* G, const float* conv_w, const float* conv_b, const float* b_i, const float* b_f, ...
;     ...
;         LAS unsigned char* wt = (LAS unsigned char*)Ps + (wid * 16) * (LROW * 2);
; #pragma unroll
;         for (int i = 0; i < 4; ++i) { const int q = lane + 64 * i; *(LAS u32x4*)(wt + (q >> 4) * (LROW * 2) + (q & 15) * 16) = ogr[i]; }
;         asm volatile("s_waitcnt lgkmcnt(0)" ::: "memory");
	v_mfma_f32_16x16x32_bf16 v[16:19], v[52:55], v[48:51], v[16:19]
	ds_read_b128 v[52:55], v225
	s_waitcnt lgkmcnt(0)
	v_mfma_f32_16x16x32_bf16 v[20:23], v[52:55], v[48:51], v[20:23]
	ds_read_b128 v[52:55], v226
	s_waitcnt lgkmcnt(0)
	v_mfma_f32_16x16x32_bf16 v[24:27], v[52:55], v[48:51], v[24:27]
	ds_read_b128 v[52:55], v227
	s_waitcnt lgkmcnt(0)
	v_mfma_f32_16x16x32_bf16 v[28:31], v[52:55], v[48:51], v[28:31]
	ds_read_b128 v[52:55], v228
	s_waitcnt lgkmcnt(0)
	v_mfma_f32_16x16x32_bf16 v[32:35], v[52:55], v[48:51], v[32:35]
	ds_read_b128 v[52:55], v229
	s_waitcnt lgkmcnt(0)
	v_mfma_f32_16x16x32_bf16 v[36:39], v[52:55], v[48:51], v[36:39]
	ds_read_b128 v[52:55], v230
	s_waitcnt lgkmcnt(0)
	v_mfma_f32_16x16x32_bf16 v[40:43], v[52:55], v[48:51], v[40:43]
	ds_read_b128 v[52:55], v231
	s_waitcnt lgkmcnt(0)
	v_mfma_f32_16x16x32_bf16 v[44:47], v[52:55], v[48:51], v[44:47]
	ds_read_b128 v[48:51], v98 offset:34880
	ds_read_b128 v[52:55], v224 offset:64
	s_waitcnt lgkmcnt(0)
	v_mfma_f32_16x16x32_bf16 v[16:19], v[52:55], v[48:51], v[16:19]
	ds_read_b128 v[52:55], v225 offset:64
	s_waitcnt lgkmcnt(0)
	v_mfma_f32_16x16x32_bf16 v[20:23], v[52:55], v[48:51], v[20:23]
	ds_read_b128 v[52:55], v226 offset:64
	s_waitcnt lgkmcnt(0)
	v_mfma_f32_16x16x32_bf16 v[24:27], v[52:55], v[48:51], v[24:27]
	ds_read_b128 v[52:55], v227 offset:64
	s_waitcnt lgkmcnt(0)
	v_mfma_f32_16x16x32_bf16 v[28:31], v[52:55], v[48:51], v[28:31]
	ds_read_b128 v[52:55], v228 offset:64
	s_waitcnt lgkmcnt(0)
	v_mfma_f32_16x16x32_bf16 v[32:35], v[52:55], v[48:51], v[32:35]
	ds_read_b128 v[52:55], v229 offset:64
	s_waitcnt lgkmcnt(0)
	v_mfma_f32_16x16x32_bf16 v[36:39], v[52:55], v[48:51], v[36:39]
	ds_read_b128 v[52:55], v230 offset:64
	s_waitcnt lgkmcnt(0)
	v_mfma_f32_16x16x32_bf16 v[40:43], v[52:55], v[48:51], v[40:43]
	ds_read_b128 v[52:55], v231 offset:64
	s_waitcnt lgkmcnt(0)
	v_mfma_f32_16x16x32_bf16 v[44:47], v[52:55], v[48:51], v[44:47]
	ds_read_b128 v[48:51], v98 offset:34944
	ds_read_b128 v[52:55], v224 offset:128
	s_waitcnt lgkmcnt(0)
	v_mfma_f32_16x16x32_bf16 v[16:19], v[52:55], v[48:51], v[16:19]
	ds_read_b128 v[52:55], v225 offset:128
	s_waitcnt lgkmcnt(0)
	v_mfma_f32_16x16x32_bf16 v[20:23], v[52:55], v[48:51], v[20:23]
	ds_read_b128 v[52:55], v226 offset:128
	s_waitcnt lgkmcnt(0)
	v_mfma_f32_16x16x32_bf16 v[24:27], v[52:55], v[48:51], v[24:27]
	ds_read_b128 v[52:55], v227 offset:128
	s_waitcnt lgkmcnt(0)
	v_mfma_f32_16x16x32_bf16 v[28:31], v[52:55], v[48:51], v[28:31]
	ds_read_b128 v[52:55], v228 offset:128
	s_waitcnt lgkmcnt(0)
	v_mfma_f32_16x16x32_bf16 v[32:35], v[52:55], v[48:51], v[32:35]
	ds_read_b128 v[52:55], v229 offset:128
	s_waitcnt lgkmcnt(0)
	v_mfma_f32_16x16x32_bf16 v[36:39], v[52:55], v[48:51], v[36:39]
	ds_read_b128 v[52:55], v230 offset:128
	s_waitcnt lgkmcnt(0)
	v_mfma_f32_16x16x32_bf16 v[40:43], v[52:55], v[48:51], v[40:43]
	ds_read_b128 v[52:55], v231 offset:128
	s_waitcnt lgkmcnt(0)
	v_mfma_f32_16x16x32_bf16 v[44:47], v[52:55], v[48:51], v[44:47]
	ds_read_b128 v[48:51], v98 offset:35008
	ds_read_b128 v[52:55], v224 offset:192
	s_waitcnt lgkmcnt(0)
	v_mfma_f32_16x16x32_bf16 v[16:19], v[52:55], v[48:51], v[16:19]
	ds_read_b128 v[52:55], v225 offset:192
	s_waitcnt lgkmcnt(0)
	v_mfma_f32_16x16x32_bf16 v[20:23], v[52:55], v[48:51], v[20:23]
	ds_read_b128 v[52:55], v226 offset:192
	s_waitcnt lgkmcnt(0)
	v_mfma_f32_16x16x32_bf16 v[24:27], v[52:55], v[48:51], v[24:27]
	ds_read_b128 v[52:55], v227 offset:192
	s_waitcnt lgkmcnt(0)
	v_mfma_f32_16x16x32_bf16 v[28:31], v[52:55], v[48:51], v[28:31]
	ds_read_b128 v[52:55], v228 offset:192
	s_waitcnt lgkmcnt(0)
	v_mfma_f32_16x16x32_bf16 v[32:35], v[52:55], v[48:51], v[32:35]
	ds_read_b128 v[52:55], v229 offset:192
	s_waitcnt lgkmcnt(0)
	v_mfma_f32_16x16x32_bf16 v[36:39], v[52:55], v[48:51], v[36:39]
	ds_read_b128 v[52:55], v230 offset:192
	s_waitcnt lgkmcnt(0)
	v_mfma_f32_16x16x32_bf16 v[40:43], v[52:55], v[48:51], v[40:43]
	ds_read_b128 v[52:55], v231 offset:192
	s_waitcnt lgkmcnt(0)
	s_waitcnt vmcnt(3)
	ds_write_b128 v233, v[0:3] offset:34816
	s_waitcnt vmcnt(2)
	ds_write_b128 v233, v[4:7] offset:35904
	s_waitcnt vmcnt(1)
	ds_write_b128 v233, v[8:11] offset:36992
	s_waitcnt vmcnt(0)
	ds_write_b128 v233, v[12:15] offset:38080
	s_waitcnt lgkmcnt(4)
	v_mfma_f32_16x16x32_bf16 v[44:47], v[52:55], v[48:51], v[44:47]
	v_div_scale_f32 v48, s[8:9], v80, v80, 1.0
	v_rcp_f32_e32 v49, v48
	s_mov_b32 s8, 0x800000
	s_mov_b32 s9, s79
	s_waitcnt lgkmcnt(0)
; #define LAS __attribute__((address_space(3)))
; #define MFMA16(a, b, c) __builtin_amdgcn_mfma_f32_16x16x32_bf16((a), (b), (c), 0, 0, 0)
; #define TR_LD8(img, e, p) (*(const LAS bf16x8*)((const LAS unsigned char*)(img) + tr_piece((e), (p))))
; template <int DIR>
; __device__ __forceinline__ void mlstm_dir(const f32x4 (&S)[8], f32x4 (&acc)[8], f32x4 (&hs)[8], LAS bf16_t* Ps, const LAS bf16_t* Vt, const LAS float* fl, int wid, int fr, int fq) {
;     ...
;     const float den = rsum + si * nq[DIR * 128 + t], scl = 1.f / fmaxf(fabsf(den), 1.f);
; #pragma unroll
;     for (int n = 0; n < 8; ++n) acc[n] *= si;
;     asm volatile("s_waitcnt lgkmcnt(0)" ::: "memory");
; #pragma unroll
;     for (int kk = 0; kk < 4; ++kk) {
;         const bf16x8 p = *(const LAS bf16x8*)(Ps + (wid * 16 + fr) * LROW + kk * 32 + fq * 8);
; #pragma unroll
;         for (int n = 0; n < 8; ++n) { const bf16x8 vf = TR_LD8(Vt, n * 16 + fr, kk * 4 + fq); acc[n] = MFMA16(vf, p, acc[n]); }
;     }
; #pragma unroll
;     for (int n = 0; n < 8; ++n) hs[n] += acc[n] * scl;
; __device__ __forceinline__ void mlstm_passC(LAS unsigned char* lds, const bf16_t* Z, const float* G, const float* conv_w, const float* conv_b, const float* b_i, const float* b_f, ...
;     ...
;         float s = 0.f;
; #pragma unroll
;         for (int n = 0; n < 8; ++n) s += (hs[n][0] + hs[n][1]) + (hs[n][2] + hs[n][3]);
;         s += __shfl_xor(s, 16); s += __shfl_xor(s, 32);
;         const float mu = s * (1.f / 128.f); float q = 0.f;
; #pragma unroll
;         for (int n = 0; n < 8; ++n) { const f32x4 d = hs[n] - mu; q += (d[0] * d[0] + d[1] * d[1]) + (d[2] * d[2] + d[3] * d[3]); }
;         q += __shfl_xor(q, 16); q += __shfl_xor(q, 32);
;         const float rstd = rsqrtf(q * (1.f / 128.f) + EPS);
;         LAS unsigned char* wt = (LAS unsigned char*)Ps + (wid * 16) * (LROW * 2);
; #pragma unroll
;         for (int i = 0; i < 4; ++i) { const int q = lane + 64 * i; *(LAS u32x4*)(wt + (q >> 4) * (LROW * 2) + (q & 15) * 16) = ogr[i]; }
;         asm volatile("s_waitcnt lgkmcnt(0)" ::: "memory");
;         const float* nw = norm_w + h * 128 + fq * 4;
;         LAS unsigned char* urow = wt + fr * (LROW * 2) + fq * 8;
; #pragma unroll
;         for (int n = 0; n < 8; ++n) {
;             LAS u32x2* up = (LAS u32x2*)(urow + n * 32);
;             const u32x2 og = *up; const f32x4 wv = *(const f32x4*)(nw + n * 16);
	v_fma_f32 v50, -v48, v49, 1.0
	v_fmac_f32_e32 v49, v50, v49
	v_div_scale_f32 v50, vcc, 1.0, v80, 1.0
	v_mul_f32_e32 v51, v50, v49
	v_fma_f32 v52, -v48, v51, v50
	v_fmac_f32_e32 v51, v52, v49
	v_fma_f32 v48, -v48, v51, v50
	v_div_fmas_f32 v48, v48, v49, v51
	v_div_fixup_f32 v64, v48, v80, 1.0
	v_pk_fma_f32 v[62:63], v[64:65], v[16:17], v[144:145] op_sel_hi:[0,1,1]
	v_pk_fma_f32 v[58:59], v[64:65], v[20:21], v[140:141] op_sel_hi:[0,1,1]
	v_pk_fma_f32 v[60:61], v[64:65], v[18:19], v[148:149] op_sel_hi:[0,1,1]
	v_pk_fma_f32 v[56:57], v[64:65], v[22:23], v[146:147] op_sel_hi:[0,1,1]
	v_pk_fma_f32 v[48:49], v[64:65], v[30:31], v[138:139] op_sel_hi:[0,1,1]
	v_pk_fma_f32 v[50:51], v[64:65], v[28:29], v[132:133] op_sel_hi:[0,1,1]
	v_pk_fma_f32 v[28:29], v[64:65], v[34:35], v[134:135] op_sel_hi:[0,1,1]
	v_pk_fma_f32 v[30:31], v[64:65], v[32:33], v[128:129] op_sel_hi:[0,1,1]
	v_mov_b32_e32 v32, v62
	v_mov_b32_e32 v33, v58
	v_mov_b32_e32 v34, v63
	v_mov_b32_e32 v35, v59
	v_pk_fma_f32 v[52:53], v[64:65], v[26:27], v[142:143] op_sel_hi:[0,1,1]
	v_pk_fma_f32 v[26:27], v[64:65], v[36:37], v[94:95] op_sel_hi:[0,1,1]
	v_pk_add_f32 v[32:33], v[32:33], v[34:35]
	v_mov_b32_e32 v34, v60
	v_mov_b32_e32 v35, v56
	v_mov_b32_e32 v36, v61
	v_mov_b32_e32 v37, v57
	v_pk_fma_f32 v[54:55], v[64:65], v[24:25], v[136:137] op_sel_hi:[0,1,1]
	v_pk_add_f32 v[34:35], v[34:35], v[36:37]
	v_mov_b32_e32 v36, v54
	v_pk_add_f32 v[32:33], v[32:33], v[34:35]
	v_pk_mov_b32 v[34:35], v[54:55], v[52:53] op_sel:[1,0]
	v_mov_b32_e32 v37, v53
	v_pk_add_f32 v[34:35], v[34:35], v[36:37]
	v_pk_add_f32 v[32:33], v[32:33], v[32:33] op_sel:[0,1] op_sel_hi:[1,0]
	v_pk_add_f32 v[34:35], v[34:35], v[34:35] op_sel:[0,1] op_sel_hi:[1,0]
	v_pk_fma_f32 v[24:25], v[64:65], v[38:39], v[130:131] op_sel_hi:[0,1,1]
	v_add_f32_e32 v36, v50, v51
	v_add_f32_e32 v38, v48, v49
	v_mov_b32_e32 v33, v30
	v_mov_b32_e32 v35, v31
	v_mov_b32_e32 v37, v28
	v_mov_b32_e32 v39, v29
	v_pk_add_f32 v[32:33], v[32:33], v[34:35]
	v_pk_add_f32 v[34:35], v[36:37], v[38:39]
	v_mov_b32_e32 v36, v26
	v_pk_add_f32 v[32:33], v[32:33], v[34:35]
	v_pk_mov_b32 v[34:35], v[26:27], v[24:25] op_sel:[1,0]
	v_mov_b32_e32 v37, v25
	v_pk_add_f32 v[34:35], v[34:35], v[36:37]
	v_pk_fma_f32 v[20:21], v[64:65], v[42:43], v[126:127] op_sel_hi:[0,1,1]
	v_pk_fma_f32 v[22:23], v[64:65], v[40:41], v[90:91] op_sel_hi:[0,1,1]
	v_pk_fma_f32 v[16:17], v[64:65], v[46:47], v[92:93] op_sel_hi:[0,1,1]
	v_pk_fma_f32 v[18:19], v[64:65], v[44:45], v[88:89] op_sel_hi:[0,1,1]
	v_pk_add_f32 v[32:33], v[32:33], v[32:33] op_sel:[0,1] op_sel_hi:[1,0]
	v_pk_add_f32 v[34:35], v[34:35], v[34:35] op_sel:[0,1] op_sel_hi:[1,0]
	v_add_f32_e32 v36, v22, v23
	v_add_f32_e32 v38, v20, v21
	v_mov_b32_e32 v33, v18
	v_mov_b32_e32 v35, v19
	v_mov_b32_e32 v37, v16
	v_mov_b32_e32 v39, v17
	v_pk_add_f32 v[32:33], v[32:33], v[34:35]
	v_pk_add_f32 v[34:35], v[36:37], v[38:39]
	v_add_u32_e32 v8, 0x8800, v234
	v_pk_add_f32 v[32:33], v[32:33], v[34:35]
	ds_read2_b64 v[10:13], v8 offset1:4
	v_add_f32_e32 v32, v32, v33
	ds_bpermute_b32 v33, v115, v32
	s_waitcnt lgkmcnt(0)
	v_add_f32_e32 v32, v32, v33
	ds_bpermute_b32 v33, v117, v32
	s_waitcnt lgkmcnt(0)
	v_add_f32_e32 v44, v32, v33
	v_fmamk_f32 v32, v44, 0xbc000000, v61
	v_fmamk_f32 v34, v44, 0xbc000000, v63
	v_fmamk_f32 v33, v44, 0xbc000000, v57
	v_fmac_f32_e32 v56, 0xbc000000, v44
	v_fmamk_f32 v35, v44, 0xbc000000, v59
	v_fmac_f32_e32 v58, 0xbc000000, v44
	v_fmac_f32_e32 v60, 0xbc000000, v44
	v_fmac_f32_e32 v62, 0xbc000000, v44
	v_mov_b32_e32 v63, v58
	v_pk_mul_f32 v[36:37], v[34:35], v[34:35]
	v_mov_b32_e32 v61, v56
	v_pk_mul_f32 v[38:39], v[32:33], v[32:33]
	v_pk_fma_f32 v[36:37], v[62:63], v[62:63], v[36:37]
	v_pk_fma_f32 v[38:39], v[60:61], v[60:61], v[38:39]
	v_fmamk_f32 v55, v44, 0xbc000000, v55
	v_pk_add_f32 v[36:37], v[36:37], v[38:39]
	v_fmac_f32_e32 v54, 0xbc000000, v44
	v_fmamk_f32 v53, v44, 0xbc000000, v53
	v_fmac_f32_e32 v52, 0xbc000000, v44
	v_pk_add_f32 v[36:37], v[36:37], v[36:37] op_sel_hi:[0,1]
	v_pk_mul_f32 v[38:39], v[52:53], v[52:53]
	v_pk_mul_f32 v[40:41], v[54:55], v[54:55]
	v_fmac_f32_e32 v50, 0xbc000000, v44
	v_pk_mov_b32 v[42:43], v[40:41], v[38:39] op_sel:[1,0]
	v_mov_b32_e32 v41, v39
	v_fmamk_f32 v51, v44, 0xbc000000, v51
	v_fmac_f32_e32 v48, 0xbc000000, v44
	v_mul_f32_e32 v36, v50, v50
	v_pk_add_f32 v[38:39], v[42:43], v[40:41]
	v_fmamk_f32 v49, v44, 0xbc000000, v49
	v_pk_fma_f32 v[40:41], v[50:51], v[50:51], v[36:37] op_sel_hi:[1,1,0]
	v_mul_f32_e32 v36, v48, v48
	v_pk_add_f32 v[38:39], v[38:39], v[38:39] op_sel_hi:[0,1]
	v_pk_fma_f32 v[42:43], v[48:49], v[48:49], v[36:37] op_sel_hi:[1,1,0]
	v_fmamk_f32 v29, v44, 0xbc000000, v29
	v_fmac_f32_e32 v28, 0xbc000000, v44
	v_fmamk_f32 v31, v44, 0xbc000000, v31
	v_fmac_f32_e32 v30, 0xbc000000, v44
	v_mul_f32_e32 v40, v30, v30
	v_mul_f32_e32 v42, v31, v31
	v_mul_f32_e32 v38, v28, v28
	v_mul_f32_e32 v36, v29, v29
	v_pk_add_f32 v[40:41], v[40:41], v[42:43]
	v_pk_add_f32 v[36:37], v[38:39], v[36:37]
	v_fmamk_f32 v27, v44, 0xbc000000, v27
	v_pk_add_f32 v[36:37], v[40:41], v[36:37]
	v_fmac_f32_e32 v26, 0xbc000000, v44
	v_fmamk_f32 v25, v44, 0xbc000000, v25
	v_fmac_f32_e32 v24, 0xbc000000, v44
	v_pk_add_f32 v[36:37], v[36:37], v[36:37] op_sel_hi:[0,1]
	v_pk_mul_f32 v[38:39], v[24:25], v[24:25]
	v_pk_mul_f32 v[40:41], v[26:27], v[26:27]
	v_fmac_f32_e32 v22, 0xbc000000, v44
	v_pk_mov_b32 v[42:43], v[40:41], v[38:39] op_sel:[1,0]
	v_mov_b32_e32 v41, v39
	v_fmamk_f32 v23, v44, 0xbc000000, v23
	v_fmac_f32_e32 v20, 0xbc000000, v44
	v_mul_f32_e32 v36, v22, v22
	v_pk_add_f32 v[38:39], v[42:43], v[40:41]
	v_fmamk_f32 v21, v44, 0xbc000000, v21
	v_pk_fma_f32 v[40:41], v[22:23], v[22:23], v[36:37] op_sel_hi:[1,1,0]
	v_mul_f32_e32 v36, v20, v20
	v_pk_add_f32 v[38:39], v[38:39], v[38:39] op_sel_hi:[0,1]
	v_pk_fma_f32 v[42:43], v[20:21], v[20:21], v[36:37] op_sel_hi:[1,1,0]
	v_fmamk_f32 v17, v44, 0xbc000000, v17
	v_fmac_f32_e32 v16, 0xbc000000, v44
	v_fmamk_f32 v19, v44, 0xbc000000, v19
	v_fmac_f32_e32 v18, 0xbc000000, v44
	v_mul_f32_e32 v40, v18, v18
	v_mul_f32_e32 v42, v19, v19
	v_mul_f32_e32 v38, v16, v16
	v_mul_f32_e32 v36, v17, v17
	v_pk_add_f32 v[40:41], v[40:41], v[42:43]
	v_pk_add_f32 v[36:37], v[38:39], v[36:37]
	s_nop 0
	v_pk_add_f32 v[36:37], v[40:41], v[36:37]
	s_nop 0
	v_add_f32_e32 v36, v36, v37
	ds_bpermute_b32 v37, v115, v36
	s_waitcnt lgkmcnt(0)
; #define LAS __attribute__((address_space(3)))
; __device__ __forceinline__ float bflo(unsigned v) { return __uint_as_float(v << 16); }
; __device__ __forceinline__ float bfhi(unsigned v) { return __uint_as_float(v & 0xffff0000u); }
; __device__ __forceinline__ float sigmoid_f(float x) { return __builtin_amdgcn_rcpf(1.f + __expf(-x)); }
; __device__ __forceinline__ void mlstm_passC(LAS unsigned char* lds, const bf16_t* Z, const float* G, const float* conv_w, const float* conv_b, const float* b_i, const float* b_f, ...
;     ...
;         const float rstd = rsqrtf(q * (1.f / 128.f) + EPS);
;         LAS unsigned char* wt = (LAS unsigned char*)Ps + (wid * 16) * (LROW * 2);
; #pragma unroll
;         for (int i = 0; i < 4; ++i) { const int q = lane + 64 * i; *(LAS u32x4*)(wt + (q >> 4) * (LROW * 2) + (q & 15) * 16) = ogr[i]; }
;         asm volatile("s_waitcnt lgkmcnt(0)" ::: "memory");
;         const float* nw = norm_w + h * 128 + fq * 4;
;         LAS unsigned char* urow = wt + fr * (LROW * 2) + fq * 8;
; #pragma unroll
;         for (int n = 0; n < 8; ++n) {
;             LAS u32x2* up = (LAS u32x2*)(urow + n * 32);
;             const u32x2 og = *up; const f32x4 wv = *(const f32x4*)(nw + n * 16);
;             const float o0 = (hs[n][0] - mu) * rstd * wv[0] * sigmoid_f(bflo(og.x)), o1 = (hs[n][1] - mu) * rstd * wv[1] * sigmoid_f(bfhi(og.x));
;             const float o2 = (hs[n][2] - mu) * rstd * wv[2] * sigmoid_f(bflo(og.y)), o3 = (hs[n][3] - mu) * rstd * wv[3] * sigmoid_f(bfhi(og.y));
;             u32x2 w; w.x = pk2(o0, o1); w.y = pk2(o2, o3); *up = w;
	v_add_f32_e32 v36, v36, v37
	ds_bpermute_b32 v37, v117, v36
	s_waitcnt lgkmcnt(0)
	v_add_f32_e32 v36, v36, v37
	v_fmamk_f32 v36, v36, 0x3c000000, v232
	v_cmp_gt_f32_e32 vcc, s8, v36
	s_lshl_b32 s8, s21, 2
	v_lshl_add_u64 v[4:5], v[110:111], 0, s[8:9]
	global_load_dwordx4 v[0:3], v[4:5], off
	global_load_dwordx4 v[64:67], v[4:5], off offset:64
	global_load_dwordx4 v[72:75], v[4:5], off offset:128
	global_load_dwordx4 v[76:79], v[4:5], off offset:192
	global_load_dwordx4 v[84:87], v[4:5], off offset:256
	global_load_dwordx4 v[88:91], v[4:5], off offset:320
	global_load_dwordx4 v[92:95], v[4:5], off offset:384
	global_load_dwordx4 v[128:131], v[4:5], off offset:448
	v_mul_f32_e32 v37, 0x4b800000, v36
	v_cndmask_b32_e32 v36, v36, v37, vcc
	v_rsq_f32_e32 v36, v36
	s_cmpk_lt_i32 s2, 0x600
	v_mul_f32_e32 v37, 0x45800000, v36
	v_cndmask_b32_e32 v9, v36, v37, vcc
	v_mul_f32_e32 v6, v62, v9
	s_waitcnt vmcnt(0)
	v_mul_f32_e32 v0, v0, v6
	v_lshlrev_b32_e32 v6, 16, v10
	v_mul_f32_e32 v6, 0xbfb8aa3b, v6
	v_exp_f32_e32 v6, v6
	s_nop 0
	v_add_f32_e32 v6, 1.0, v6
	v_rcp_f32_e32 v6, v6
	s_nop 0
	v_mul_f32_e32 v0, v6, v0
	v_mul_f32_e32 v6, v34, v9
	v_mul_f32_e32 v1, v1, v6
	v_and_b32_e32 v6, 0xffff0000, v10
	v_mul_f32_e32 v6, 0xbfb8aa3b, v6
	v_exp_f32_e32 v6, v6
	v_add_u32_e32 v0, 0x8000, v0
	v_mul_f32_e32 v10, v58, v9
	v_add_f32_e32 v6, 1.0, v6
	v_rcp_f32_e32 v6, v6
	s_nop 0
	v_mul_f32_e32 v1, v6, v1
	v_mul_f32_e32 v6, v60, v9
	v_mul_f32_e32 v2, v2, v6
	v_lshlrev_b32_e32 v6, 16, v11
	v_mul_f32_e32 v6, 0xbfb8aa3b, v6
	v_exp_f32_e32 v6, v6
	v_add_u32_e32 v1, 0x8000, v1
	v_add_f32_e32 v6, 1.0, v6
	v_rcp_f32_e32 v6, v6
	s_nop 0
	v_mul_f32_e32 v2, v6, v2
	v_mul_f32_e32 v6, v32, v9
	v_mul_f32_e32 v3, v3, v6
	v_and_b32_e32 v6, 0xffff0000, v11
	v_mul_f32_e32 v6, 0xbfb8aa3b, v6
	v_exp_f32_e32 v6, v6
	s_nop 0
	v_add_f32_e32 v6, 1.0, v6
	v_rcp_f32_e32 v6, v6
	s_nop 0
	v_mul_f32_e32 v3, v6, v3
	v_perm_b32 v6, v1, v0, s0
	v_add_u32_e32 v0, 0x8000, v2
	v_add_u32_e32 v1, 0x8000, v3
	v_perm_b32 v7, v1, v0, s0
	v_mov_b32_e32 v0, v64
	v_mov_b32_e32 v1, v65
	v_mov_b32_e32 v2, v66
	v_mov_b32_e32 v3, v67
	s_waitcnt vmcnt(0)
	v_mul_f32_e32 v0, v0, v10
	v_lshlrev_b32_e32 v10, 16, v12
	v_mul_f32_e32 v10, 0xbfb8aa3b, v10
	v_exp_f32_e32 v10, v10
	s_nop 0
	v_add_f32_e32 v10, 1.0, v10
	v_rcp_f32_e32 v10, v10
	s_nop 0
	v_mul_f32_e32 v0, v10, v0
	v_mul_f32_e32 v10, v35, v9
	v_mul_f32_e32 v1, v1, v10
	v_and_b32_e32 v10, 0xffff0000, v12
	v_mul_f32_e32 v10, 0xbfb8aa3b, v10
	v_exp_f32_e32 v10, v10
	v_add_u32_e32 v0, 0x8000, v0
	v_add_f32_e32 v10, 1.0, v10
	v_rcp_f32_e32 v10, v10
	s_nop 0
	v_mul_f32_e32 v1, v10, v1
	v_mul_f32_e32 v10, v56, v9
	v_mul_f32_e32 v2, v2, v10
	v_lshlrev_b32_e32 v10, 16, v13
	v_mul_f32_e32 v10, 0xbfb8aa3b, v10
	v_exp_f32_e32 v10, v10
	v_add_u32_e32 v1, 0x8000, v1
	v_perm_b32 v0, v1, v0, s0
	v_add_f32_e32 v10, 1.0, v10
	v_rcp_f32_e32 v10, v10
	s_nop 0
	v_mul_f32_e32 v2, v10, v2
	v_mul_f32_e32 v10, v33, v9
	v_mul_f32_e32 v3, v3, v10
	v_and_b32_e32 v10, 0xffff0000, v13
	v_mul_f32_e32 v10, 0xbfb8aa3b, v10
	v_exp_f32_e32 v10, v10
	v_add_u32_e32 v1, 0x8000, v2
	v_add_f32_e32 v10, 1.0, v10
	v_rcp_f32_e32 v10, v10
	s_nop 0
	v_mul_f32_e32 v3, v10, v3
	v_mov_b32_e32 v10, v72
	v_mov_b32_e32 v11, v73
	v_mov_b32_e32 v12, v74
	v_mov_b32_e32 v13, v75
	v_add_u32_e32 v2, 0x8000, v3
	v_perm_b32 v1, v2, v1, s0
	ds_write2_b64 v8, v[6:7], v[0:1] offset1:4
	ds_read2_b64 v[0:3], v8 offset0:8 offset1:12
	v_mul_f32_e32 v6, v54, v9
	s_waitcnt lgkmcnt(0)
	v_lshlrev_b32_e32 v7, 16, v0
	v_mul_f32_e32 v7, 0xbfb8aa3b, v7
	v_exp_f32_e32 v7, v7
	v_and_b32_e32 v0, 0xffff0000, v0
	v_mul_f32_e32 v0, 0xbfb8aa3b, v0
	v_exp_f32_e32 v0, v0
	v_add_f32_e32 v7, 1.0, v7
	v_rcp_f32_e32 v7, v7
	v_add_f32_e32 v0, 1.0, v0
	v_rcp_f32_e32 v0, v0
	s_waitcnt vmcnt(0)
	v_mul_f32_e32 v6, v10, v6
	v_lshlrev_b32_e32 v10, 16, v1
	v_mul_f32_e32 v10, 0xbfb8aa3b, v10
	v_exp_f32_e32 v10, v10
	v_and_b32_e32 v1, 0xffff0000, v1
	v_mul_f32_e32 v1, 0xbfb8aa3b, v1
	v_exp_f32_e32 v1, v1
	v_add_f32_e32 v10, 1.0, v10
	v_mul_f32_e32 v6, v7, v6
	v_mul_f32_e32 v7, v55, v9
	v_rcp_f32_e32 v10, v10
	v_mul_f32_e32 v7, v11, v7
	v_add_f32_e32 v1, 1.0, v1
	v_mul_f32_e32 v0, v0, v7
	v_mul_f32_e32 v7, v52, v9
	v_rcp_f32_e32 v1, v1
	v_mul_f32_e32 v7, v12, v7
	v_mul_f32_e32 v7, v10, v7
	v_mul_f32_e32 v10, v53, v9
	v_mul_f32_e32 v10, v13, v10
	v_mul_f32_e32 v1, v1, v10
	v_mov_b32_e32 v10, v76
	v_mov_b32_e32 v11, v77
	v_mov_b32_e32 v12, v78
	v_mov_b32_e32 v13, v79
	v_add_u32_e32 v6, 0x8000, v6
	v_add_u32_e32 v0, 0x8000, v0
	v_perm_b32 v0, v0, v6, s0
	v_add_u32_e32 v6, 0x8000, v7
	v_lshlrev_b32_e32 v7, 16, v2
	v_mul_f32_e32 v7, 0xbfb8aa3b, v7
	v_add_u32_e32 v1, 0x8000, v1
	v_exp_f32_e32 v7, v7
	v_and_b32_e32 v2, 0xffff0000, v2
	v_perm_b32 v1, v1, v6, s0
	v_mul_f32_e32 v6, v50, v9
	v_mul_f32_e32 v2, 0xbfb8aa3b, v2
	v_exp_f32_e32 v2, v2
	v_add_f32_e32 v7, 1.0, v7
	v_rcp_f32_e32 v7, v7
	v_add_f32_e32 v2, 1.0, v2
	v_rcp_f32_e32 v2, v2
	s_waitcnt vmcnt(0)
	v_mul_f32_e32 v6, v10, v6
	v_lshlrev_b32_e32 v10, 16, v3
	v_mul_f32_e32 v10, 0xbfb8aa3b, v10
	v_exp_f32_e32 v10, v10
	v_and_b32_e32 v3, 0xffff0000, v3
	v_mul_f32_e32 v3, 0xbfb8aa3b, v3
	v_exp_f32_e32 v3, v3
	v_add_f32_e32 v10, 1.0, v10
	v_mul_f32_e32 v6, v7, v6
	v_mul_f32_e32 v7, v51, v9
	v_rcp_f32_e32 v10, v10
	v_mul_f32_e32 v7, v11, v7
	v_add_f32_e32 v3, 1.0, v3
	v_mul_f32_e32 v2, v2, v7
	v_mul_f32_e32 v7, v48, v9
	v_rcp_f32_e32 v3, v3
	v_mul_f32_e32 v7, v12, v7
	v_mul_f32_e32 v7, v10, v7
	v_mul_f32_e32 v10, v49, v9
	v_mul_f32_e32 v10, v13, v10
	v_mul_f32_e32 v3, v3, v10
	v_mov_b32_e32 v10, v84
	v_mov_b32_e32 v11, v85
	v_mov_b32_e32 v12, v86
	v_mov_b32_e32 v13, v87
	v_add_u32_e32 v6, 0x8000, v6
	v_add_u32_e32 v2, 0x8000, v2
	v_perm_b32 v2, v2, v6, s0
	v_add_u32_e32 v6, 0x8000, v7
	v_add_u32_e32 v3, 0x8000, v3
	v_perm_b32 v3, v3, v6, s0
	ds_write2_b64 v8, v[0:1], v[2:3] offset0:8 offset1:12
	ds_read2_b64 v[0:3], v8 offset0:16 offset1:20
	v_mul_f32_e32 v6, v30, v9
	s_waitcnt lgkmcnt(0)
; #define LAS __attribute__((address_space(3)))
; __device__ __forceinline__ float bflo(unsigned v) { return __uint_as_float(v << 16); }
; __device__ __forceinline__ float bfhi(unsigned v) { return __uint_as_float(v & 0xffff0000u); }
; __device__ __forceinline__ float sigmoid_f(float x) { return __builtin_amdgcn_rcpf(1.f + __expf(-x)); }
; __device__ __forceinline__ void mlstm_passC(LAS unsigned char* lds, const bf16_t* Z, const float* G, const float* conv_w, const float* conv_b, const float* b_i, const float* b_f, ...
;     ...
;         const float* nw = norm_w + h * 128 + fq * 4;
;         LAS unsigned char* urow = wt + fr * (LROW * 2) + fq * 8;
; #pragma unroll
;         for (int n = 0; n < 8; ++n) {
;             LAS u32x2* up = (LAS u32x2*)(urow + n * 32);
;             const u32x2 og = *up; const f32x4 wv = *(const f32x4*)(nw + n * 16);
;             const float o0 = (hs[n][0] - mu) * rstd * wv[0] * sigmoid_f(bflo(og.x)), o1 = (hs[n][1] - mu) * rstd * wv[1] * sigmoid_f(bfhi(og.x));
;             const float o2 = (hs[n][2] - mu) * rstd * wv[2] * sigmoid_f(bflo(og.y)), o3 = (hs[n][3] - mu) * rstd * wv[3] * sigmoid_f(bfhi(og.y));
;             u32x2 w; w.x = pk2(o0, o1); w.y = pk2(o2, o3); *up = w;
;         }
;         asm volatile("s_waitcnt lgkmcnt(0)" ::: "memory");
; #pragma unroll
;         for (int i = 0; i < 4; ++i) { const int q = lane + 64 * i, r = q >> 4, p = q & 15;
;             *(u32x4*)(MIX + (size_t)(r0 + wid * 16 + r) * DM + h * 128 + p * 8) = *(const LAS u32x4*)(wt + r * (LROW * 2) + p * 16); }
;     }
;     __syncthreads();
	v_lshlrev_b32_e32 v7, 16, v0
	v_mul_f32_e32 v7, 0xbfb8aa3b, v7
	v_exp_f32_e32 v7, v7
	v_and_b32_e32 v0, 0xffff0000, v0
	v_mul_f32_e32 v0, 0xbfb8aa3b, v0
	v_exp_f32_e32 v0, v0
	v_add_f32_e32 v7, 1.0, v7
	v_rcp_f32_e32 v7, v7
	v_add_f32_e32 v0, 1.0, v0
	v_rcp_f32_e32 v0, v0
	s_waitcnt vmcnt(0)
	v_mul_f32_e32 v6, v10, v6
	v_lshlrev_b32_e32 v10, 16, v1
	v_mul_f32_e32 v10, 0xbfb8aa3b, v10
	v_exp_f32_e32 v10, v10
	v_and_b32_e32 v1, 0xffff0000, v1
	v_mul_f32_e32 v1, 0xbfb8aa3b, v1
	v_exp_f32_e32 v1, v1
	v_add_f32_e32 v10, 1.0, v10
	v_mul_f32_e32 v6, v7, v6
	v_mul_f32_e32 v7, v31, v9
	v_rcp_f32_e32 v10, v10
	v_mul_f32_e32 v7, v11, v7
	v_add_f32_e32 v1, 1.0, v1
	v_mul_f32_e32 v0, v0, v7
	v_mul_f32_e32 v7, v28, v9
	v_rcp_f32_e32 v1, v1
	v_mul_f32_e32 v7, v12, v7
	v_mul_f32_e32 v7, v10, v7
	v_mul_f32_e32 v10, v29, v9
	v_mul_f32_e32 v10, v13, v10
	v_mul_f32_e32 v1, v1, v10
	v_mov_b32_e32 v10, v88
	v_mov_b32_e32 v11, v89
	v_mov_b32_e32 v12, v90
	v_mov_b32_e32 v13, v91
	v_add_u32_e32 v6, 0x8000, v6
	v_add_u32_e32 v0, 0x8000, v0
	v_perm_b32 v0, v0, v6, s0
	v_add_u32_e32 v6, 0x8000, v7
	v_lshlrev_b32_e32 v7, 16, v2
	v_mul_f32_e32 v7, 0xbfb8aa3b, v7
	v_add_u32_e32 v1, 0x8000, v1
	v_exp_f32_e32 v7, v7
	v_and_b32_e32 v2, 0xffff0000, v2
	v_perm_b32 v1, v1, v6, s0
	v_mul_f32_e32 v6, v26, v9
	v_mul_f32_e32 v2, 0xbfb8aa3b, v2
	v_exp_f32_e32 v2, v2
	v_add_f32_e32 v7, 1.0, v7
	v_rcp_f32_e32 v7, v7
	v_add_f32_e32 v2, 1.0, v2
	v_rcp_f32_e32 v2, v2
	s_waitcnt vmcnt(0)
	v_mul_f32_e32 v6, v10, v6
	v_lshlrev_b32_e32 v10, 16, v3
	v_mul_f32_e32 v10, 0xbfb8aa3b, v10
	v_exp_f32_e32 v10, v10
	v_and_b32_e32 v3, 0xffff0000, v3
	v_mul_f32_e32 v3, 0xbfb8aa3b, v3
	v_exp_f32_e32 v3, v3
	v_add_f32_e32 v10, 1.0, v10
	v_mul_f32_e32 v6, v7, v6
	v_mul_f32_e32 v7, v27, v9
	v_rcp_f32_e32 v10, v10
	v_mul_f32_e32 v7, v11, v7
	v_add_f32_e32 v3, 1.0, v3
	v_mul_f32_e32 v2, v2, v7
	v_mul_f32_e32 v7, v24, v9
	v_rcp_f32_e32 v3, v3
	v_mul_f32_e32 v7, v12, v7
	v_mul_f32_e32 v7, v10, v7
	v_mul_f32_e32 v10, v25, v9
	v_mul_f32_e32 v10, v13, v10
	v_mul_f32_e32 v3, v3, v10
	v_mov_b32_e32 v10, v92
	v_mov_b32_e32 v11, v93
	v_mov_b32_e32 v12, v94
	v_mov_b32_e32 v13, v95
	v_add_u32_e32 v6, 0x8000, v6
	v_add_u32_e32 v2, 0x8000, v2
	v_perm_b32 v2, v2, v6, s0
	v_add_u32_e32 v6, 0x8000, v7
	v_add_u32_e32 v3, 0x8000, v3
	v_perm_b32 v3, v3, v6, s0
	ds_write2_b64 v8, v[0:1], v[2:3] offset0:16 offset1:20
	ds_read2_b64 v[0:3], v8 offset0:24 offset1:28
	v_mul_f32_e32 v6, v22, v9
	s_waitcnt lgkmcnt(0)
	v_lshlrev_b32_e32 v7, 16, v0
	v_mul_f32_e32 v7, 0xbfb8aa3b, v7
	v_exp_f32_e32 v7, v7
	v_and_b32_e32 v0, 0xffff0000, v0
	v_mul_f32_e32 v0, 0xbfb8aa3b, v0
	v_exp_f32_e32 v0, v0
	v_add_f32_e32 v7, 1.0, v7
	v_rcp_f32_e32 v7, v7
	v_add_f32_e32 v0, 1.0, v0
	v_rcp_f32_e32 v0, v0
	s_waitcnt vmcnt(0)
	v_mul_f32_e32 v6, v10, v6
	v_lshlrev_b32_e32 v10, 16, v1
	v_mul_f32_e32 v10, 0xbfb8aa3b, v10
	v_exp_f32_e32 v10, v10
	v_and_b32_e32 v1, 0xffff0000, v1
	v_mul_f32_e32 v1, 0xbfb8aa3b, v1
	v_exp_f32_e32 v1, v1
	v_add_f32_e32 v10, 1.0, v10
	v_mul_f32_e32 v6, v6, v7
	v_mul_f32_e32 v7, v23, v9
	v_rcp_f32_e32 v10, v10
	v_mul_f32_e32 v7, v11, v7
	v_add_f32_e32 v1, 1.0, v1
	v_mul_f32_e32 v0, v7, v0
	v_mul_f32_e32 v7, v20, v9
	v_rcp_f32_e32 v1, v1
	v_mul_f32_e32 v7, v12, v7
	v_mul_f32_e32 v7, v7, v10
	v_mul_f32_e32 v10, v21, v9
	v_mul_f32_e32 v10, v13, v10
	v_mul_f32_e32 v1, v10, v1
	v_add_u32_e32 v6, 0x8000, v6
	v_add_u32_e32 v0, 0x8000, v0
	v_perm_b32 v0, v0, v6, s0
	v_add_u32_e32 v6, 0x8000, v7
	v_add_u32_e32 v1, 0x8000, v1
	v_perm_b32 v1, v1, v6, s0
	v_mov_b32_e32 v4, v128
	v_mov_b32_e32 v5, v129
	v_mov_b32_e32 v6, v130
	v_mov_b32_e32 v7, v131
	v_mul_f32_e32 v10, v18, v9
	s_waitcnt vmcnt(0)
	v_mul_f32_e32 v4, v4, v10
	v_lshlrev_b32_e32 v10, 16, v2
	v_mul_f32_e32 v10, 0xbfb8aa3b, v10
	v_exp_f32_e32 v10, v10
	v_and_b32_e32 v2, 0xffff0000, v2
	v_mul_f32_e32 v2, 0xbfb8aa3b, v2
	v_exp_f32_e32 v2, v2
	v_add_f32_e32 v10, 1.0, v10
	v_rcp_f32_e32 v10, v10
	v_add_f32_e32 v2, 1.0, v2
	v_rcp_f32_e32 v2, v2
	v_mul_f32_e32 v4, v4, v10
	v_mul_f32_e32 v10, v19, v9
	v_mul_f32_e32 v5, v5, v10
	v_mul_f32_e32 v2, v5, v2
	v_mul_f32_e32 v5, v16, v9
	v_mul_f32_e32 v5, v6, v5
	v_lshlrev_b32_e32 v6, 16, v3
	v_mul_f32_e32 v6, 0xbfb8aa3b, v6
	v_exp_f32_e32 v6, v6
	v_and_b32_e32 v3, 0xffff0000, v3
	v_mul_f32_e32 v3, 0xbfb8aa3b, v3
	v_exp_f32_e32 v3, v3
	v_add_f32_e32 v6, 1.0, v6
	v_rcp_f32_e32 v6, v6
	v_add_u32_e32 v4, 0x8000, v4
	v_add_f32_e32 v3, 1.0, v3
	v_rcp_f32_e32 v3, v3
	v_mul_f32_e32 v5, v5, v6
	v_mul_f32_e32 v6, v17, v9
	v_mul_f32_e32 v6, v7, v6
	v_mul_f32_e32 v3, v6, v3
	v_add_u32_e32 v2, 0x8000, v2
	v_perm_b32 v2, v2, v4, s0
	v_add_u32_e32 v4, 0x8000, v5
	v_add_u32_e32 v3, 0x8000, v3
	v_perm_b32 v3, v3, v4, s0
	ds_write2_b64 v8, v[0:1], v[2:3] offset0:24 offset1:28
	s_waitcnt lgkmcnt(0)
	ds_read_b128 v[0:3], v235 offset:34816
	v_lshl_add_u64 v[4:5], v[112:113], 0, s[78:79]
	v_lshlrev_b64 v[6:7], 12, v[118:119]
	v_lshl_add_u64 v[6:7], v[4:5], 0, v[6:7]
	s_waitcnt lgkmcnt(0)
	global_store_dwordx4 v[6:7], v[0:3], off
	ds_read_b128 v[0:3], v235 offset:35904
	v_lshlrev_b64 v[6:7], 12, v[122:123]
	v_lshl_add_u64 v[6:7], v[4:5], 0, v[6:7]
	s_waitcnt lgkmcnt(0)
	global_store_dwordx4 v[6:7], v[0:3], off
	ds_read_b128 v[0:3], v235 offset:36992
	v_lshlrev_b64 v[6:7], 12, v[124:125]
	v_lshl_add_u64 v[6:7], v[4:5], 0, v[6:7]
	s_waitcnt lgkmcnt(0)
	global_store_dwordx4 v[6:7], v[0:3], off
	ds_read_b128 v[0:3], v235 offset:38080
	v_lshlrev_b64 v[6:7], 12, v[120:121]
	v_lshl_add_u64 v[4:5], v[4:5], 0, v[6:7]
	s_waitcnt lgkmcnt(0)
	global_store_dwordx4 v[4:5], v[0:3], off
	s_barrier
	s_cbranch_scc0 .LBB0_1018
